# scan: sum-of-squares as one transposing DPP tree + chunk prefetch given a full iteration; sample_batch: beta/decay of 8 tokens vectorised over 8 lanes
# speedup vs baseline: 1.2030x; 1.2030x over previous
.LBB0_1038:
	s_and_b64 vcc, exec, s[0:1]
	s_cbranch_vccz .LBB0_1083
	s_lshl_b32 s0, s84, 8
	s_and_b32 s14, s0, 0xfffff800
	s_lshl_b32 s8, s84, 5
	s_ashr_i32 s15, s14, 31
	s_mov_b64 s[38:39], s[28:29]
	s_and_b32 s28, s0, 0x700
	s_add_u32 s30, s68, s28
	s_addc_u32 s31, s69, 0
	s_add_u32 s34, s3, s28
	s_addc_u32 s35, s85, 0
	s_ashr_i32 s9, s8, 31
	s_lshl_b64 s[2:3], s[8:9], 14
	s_add_u32 s36, s38, s2
	s_addc_u32 s37, s39, s3
	s_add_u32 s10, s92, s28
	s_addc_u32 s11, s93, 0
	s_lshl_b64 s[0:1], s[8:9], 13
	s_add_u32 s0, s26, s0
	s_addc_u32 s1, s27, s1
	s_add_u32 s24, s66, s2
	s_addc_u32 s25, s67, s3
	s_lshl_b64 s[12:13], s[8:9], 2
	s_add_u32 s22, s78, s12
	s_addc_u32 s23, s79, s13
	s_or_b32 s2, s8, 1
	s_or_b32 s6, s14, 64
	s_ashr_i32 s3, s2, 31
	s_ashr_i32 s7, s6, 31
	s_lshl_b64 s[4:5], s[2:3], 14
	s_add_u32 s20, s38, s4
	s_addc_u32 s21, s39, s5
	s_lshl_b64 s[16:17], s[2:3], 13
	s_add_u32 s16, s26, s16
	s_addc_u32 s17, s27, s17
	s_add_u32 s18, s66, s4
	s_addc_u32 s19, s67, s5
	s_lshl_b64 s[2:3], s[2:3], 2
	s_add_u32 s4, s78, s2
	s_waitcnt vmcnt(10)
	v_mov_b32_e32 v46, v0
	v_readfirstlane_b32 s2, v0
	s_addc_u32 s5, s79, s3
	s_lshr_b32 s9, s2, 6
	v_lshlrev_b32_e32 v10, 3, v46
	v_ashrrev_i32_e32 v108, 4, v46
	v_and_b32_e32 v1, 15, v46
	s_lshl_b32 s2, s9, 4
	v_and_b32_e32 v47, 0x78, v10
	v_ashrrev_i32_e32 v109, 31, v108
	v_mov_b32_e32 v103, 0
	v_or_b32_e32 v2, s2, v1
	v_readlane_b32 s40, v245, 26
	v_lshlrev_b32_e32 v102, 1, v47
	v_lshl_add_u64 v[32:33], v[108:109], 0, s[14:15]
	s_waitcnt vmcnt(7)
	v_add_u32_e32 v49, 0x200, v46
	v_lshlrev_b32_e32 v2, 2, v2
	v_readlane_b32 s48, v245, 34
	v_readlane_b32 s49, v245, 35
	v_lshl_add_u64 v[104:105], s[30:31], 0, v[102:103]
	v_lshl_add_u64 v[106:107], s[34:35], 0, v[102:103]
	v_lshlrev_b64 v[34:35], 11, v[32:33]
	v_ashrrev_i32_e32 v112, 4, v49
	v_and_b32_e32 v48, 56, v10
	global_load_dword v128, v2, s[48:49]
	v_lshl_add_u64 v[2:3], v[104:105], 0, v[34:35]
	v_lshl_add_u64 v[6:7], v[106:107], 0, v[34:35]
	v_and_b32_e32 v110, 0xffffffc0, v10
	v_ashrrev_i32_e32 v113, 31, v112
	s_barrier
	v_lshlrev_b32_e32 v30, 1, v48
	v_mov_b32_e32 v31, v103
	global_load_dwordx4 v[2:5], v[2:3], off nt
	s_nop 0
	global_load_dwordx4 v[6:9], v[6:7], off nt
	v_ashrrev_i32_e32 v111, 31, v110
	v_lshl_add_u64 v[38:39], v[112:113], 0, s[14:15]
	v_lshl_add_u64 v[22:23], s[36:37], 0, v[30:31]
	v_lshlrev_b64 v[36:37], 1, v[110:111]
	v_lshlrev_b64 v[40:41], 11, v[38:39]
	v_lshl_add_u64 v[10:11], v[22:23], 0, v[36:37]
	v_lshl_add_u64 v[14:15], v[104:105], 0, v[40:41]
	v_lshl_add_u64 v[18:19], v[106:107], 0, v[40:41]
	v_lshlrev_b32_e32 v24, 3, v49
	v_ashrrev_i32_e32 v50, 3, v46
	global_load_dwordx4 v[10:13], v[10:11], off nt
	s_nop 0
	global_load_dwordx4 v[14:17], v[14:15], off nt
	s_nop 0
	global_load_dwordx4 v[18:21], v[18:19], off nt
	v_and_b32_e32 v114, 0xffffffc0, v24
	v_lshlrev_b32_e32 v26, 6, v50
	v_ashrrev_i32_e32 v115, 31, v114
	v_ashrrev_i32_e32 v27, 31, v26
	v_lshlrev_b64 v[42:43], 1, v[114:115]
	v_lshlrev_b64 v[44:45], 1, v[26:27]
	v_lshl_add_u64 v[22:23], v[22:23], 0, v[42:43]
	v_lshl_add_u64 v[26:27], s[0:1], 0, v[44:45]
	global_load_dwordx4 v[22:25], v[22:23], off nt
	v_lshl_add_u64 v[26:27], v[26:27], 0, v[30:31]
	global_load_dwordx4 v[26:29], v[26:27], off nt
	v_lshl_add_u64 v[116:117], s[10:11], 0, v[102:103]
	v_lshl_add_u64 v[34:35], v[116:117], 0, v[34:35]
	v_and_b32_e32 v51, 63, v46
	global_load_dwordx4 v[66:69], v[34:35], off nt
	v_lshl_add_u64 v[34:35], v[116:117], 0, v[40:41]
	s_lshl_b32 s10, s9, 9
	global_load_dwordx4 v[62:65], v[34:35], off nt
	v_lshlrev_b32_e32 v34, 2, v51
	v_mov_b32_e32 v35, v103
	s_ashr_i32 s11, s10, 31
	v_lshl_add_u64 v[40:41], s[24:25], 0, v[34:35]
	s_lshl_b64 s[24:25], s[10:11], 2
	v_lshl_add_u64 v[40:41], v[40:41], 0, s[24:25]
	s_movk_i32 s0, 0x88
	global_load_dword v156, v[40:41], off nt
	global_load_dword v157, v[40:41], off offset:256 nt
	global_load_dword v145, v[40:41], off offset:512 nt
	global_load_dword v147, v[40:41], off offset:768 nt
	global_load_dword v152, v[40:41], off offset:1024 nt
	global_load_dword v153, v[40:41], off offset:1280 nt
	global_load_dword v154, v[40:41], off offset:1536 nt
	global_load_dword v155, v[40:41], off offset:1792 nt
	global_load_dword v129, v103, s[22:23]
	v_mul_lo_u32 v40, v108, s0
	v_add_lshl_u32 v130, v40, v47, 1
	v_add_u32_e32 v40, 0, v130
	s_movk_i32 s3, 0x48
	s_waitcnt vmcnt(17)
	ds_write_b128 v40, v[2:5]
	s_waitcnt vmcnt(16)
	ds_write_b128 v40, v[6:9] offset:17408
	v_mul_lo_u32 v2, v50, s3
	v_mul_lo_u32 v3, v112, s0
	v_add_lshl_u32 v131, v2, v48, 1
	v_add_lshl_u32 v132, v3, v47, 1
	v_add_u32_e32 v2, 0, v131
	v_add_u32_e32 v3, 0, v132
	s_lshl_b32 s0, s9, 8
	v_lshrrev_b32_e32 v40, 1, v46
	s_add_i32 s15, 0, 0x1f100
	v_add_u32_e32 v41, s15, v102
	s_waitcnt vmcnt(15)
	ds_write_b128 v2, v[10:13] offset:44032
	s_waitcnt vmcnt(14)
	ds_write_b128 v3, v[14:17]
	s_waitcnt vmcnt(13)
	ds_write_b128 v3, v[18:21] offset:17408
	v_lshrrev_b32_e32 v3, 3, v49
	v_mul_lo_u32 v3, v3, s3
	v_add_lshl_u32 v133, v3, v48, 1
	v_add_u32_e32 v3, 0, v133
	s_waitcnt vmcnt(12)
	ds_write_b128 v3, v[22:25] offset:44032
	s_waitcnt vmcnt(11)
	ds_write_b128 v2, v[26:29] offset:34816
	v_lshl_add_u64 v[2:3], v[108:109], 0, s[6:7]
	v_lshlrev_b64 v[14:15], 11, v[2:3]
	v_lshl_add_u64 v[2:3], v[104:105], 0, v[14:15]
	v_lshl_add_u64 v[6:7], v[106:107], 0, v[14:15]
	v_lshl_add_u64 v[14:15], v[116:117], 0, v[14:15]
	s_waitcnt lgkmcnt(0)
	s_barrier
	global_load_dwordx4 v[2:5], v[2:3], off nt
	s_nop 0
	global_load_dwordx4 v[6:9], v[6:7], off nt
	v_lshl_add_u64 v[22:23], s[20:21], 0, v[30:31]
	global_load_dwordx4 v[238:241], v[14:15], off nt
	v_lshl_add_u64 v[14:15], v[112:113], 0, s[6:7]
	v_lshlrev_b64 v[26:27], 11, v[14:15]
	v_lshl_add_u64 v[10:11], v[22:23], 0, v[36:37]
	v_lshl_add_u64 v[14:15], v[104:105], 0, v[26:27]
	v_lshl_add_u64 v[18:19], v[106:107], 0, v[26:27]
	v_lshl_add_u64 v[26:27], v[116:117], 0, v[26:27]
	global_load_dwordx4 v[10:13], v[10:11], off nt
	s_nop 0
	global_load_dwordx4 v[14:17], v[14:15], off nt
	s_nop 0
	global_load_dwordx4 v[18:21], v[18:19], off nt
	v_lshl_add_u64 v[22:23], v[22:23], 0, v[42:43]
	global_load_dwordx4 v[246:249], v[26:27], off nt
	v_lshl_add_u64 v[26:27], s[16:17], 0, v[44:45]
	v_lshl_add_u64 v[26:27], v[26:27], 0, v[30:31]
	v_lshl_add_u64 v[28:29], s[18:19], 0, v[34:35]
	global_load_dwordx4 v[22:25], v[22:23], off nt
	v_lshl_add_u64 v[36:37], v[28:29], 0, s[24:25]
	global_load_dwordx4 v[26:29], v[26:27], off nt
	s_nop 0
	global_load_dword v230, v[36:37], off nt
	global_load_dword v231, v[36:37], off offset:256 nt
	global_load_dword v232, v[36:37], off offset:512 nt
	global_load_dword v233, v[36:37], off offset:768 nt
	global_load_dword v234, v[36:37], off offset:1024 nt
	global_load_dword v235, v[36:37], off offset:1280 nt
	global_load_dword v236, v[36:37], off offset:1536 nt
	global_load_dword v237, v[36:37], off offset:1792 nt
	global_load_dword v250, v103, s[4:5]
	s_add_i32 s6, 0, 0x1e800
	s_add_i32 s3, s6, s0
	v_and_b32_e32 v36, 7, v46
	s_lshl_b32 s0, s9, 5
	v_lshlrev_b32_e32 v37, 8, v36
	v_and_or_b32 v40, v40, 28, s0
	v_add3_u32 v136, s6, v37, v40
	v_cmp_eq_u32_e64 s[6:7], 0, v36
	s_add_i32 s9, 0, 0x1f000
	v_lshrrev_b32_e32 v36, 2, v46
	s_add_i32 s0, s15, s0
	v_add_u32_e32 v137, s9, v40
	v_and_b32_e32 v134, 12, v36
	v_lshl_add_u32 v40, v1, 1, s0
	s_movk_i32 s0, 0x110
	v_mov_b32_e32 v36, 0x1100
	v_mad_u32_u24 v138, v1, s0, v36
	s_movk_i32 s15, 0x90
	v_mov_b32_e32 v36, 0x900
	v_mad_u32_u24 v140, v1, s15, v36
	v_lshl_add_u32 v141, v134, 2, s9
	v_lshl_add_u64 v[36:37], s[26:27], 0, v[44:45]
	s_add_u32 s9, s94, s12
	v_lshl_add_u64 v[118:119], s[38:39], 0, v[30:31]
	v_lshl_add_u64 v[120:121], v[36:37], 0, v[30:31]
	v_lshl_add_u64 v[122:123], s[66:67], 0, v[34:35]
	s_addc_u32 s13, s95, s13
	v_lshlrev_b64 v[30:31], 12, v[38:39]
	v_lshlrev_b32_e32 v34, 4, v1
	s_add_u32 s12, s9, 0x130008
	v_or3_b32 v30, v30, s28, v34
	s_addc_u32 s13, s13, 0
	s_or_b32 s20, s8, 2
	v_lshl_add_u64 v[30:31], s[94:95], 0, v[30:31]
	s_mov_b64 s[8:9], 0x6b00000
	v_lshl_add_u64 v[124:125], v[30:31], 0, s[8:9]
	v_lshlrev_b64 v[30:31], 12, v[32:33]
	v_or3_b32 v30, v30, s28, v34
	s_mov_b32 s1, 0
	v_and_b32_e32 v135, 48, v46
	v_mul_u32_u24_e32 v42, 0x110, v134
	v_mul_lo_u32 v43, v108, s0
	v_mul_lo_u32 v46, v112, s0
	v_lshl_add_u64 v[30:31], s[94:95], 0, v[30:31]
	v_cmp_eq_u32_e64 s[4:5], 0, v1
	v_mul_u32_u24_e32 v102, 0x110, v1
	v_mul_u32_u24_e32 v139, 0x90, v1
	v_add_u32_e32 v142, 64, v141
	v_add_u32_e32 v143, 0x80, v141
	v_add_u32_e32 v144, 0xc0, v141
	s_mov_b32 s0, s10
	s_bitset1_b32 s14, 7
	v_lshl_add_u64 v[126:127], v[30:31], 0, s[8:9]
	v_mov_b32_e32 v146, 0x358637bd
	v_mov_b32_e32 v148, 0x260
	v_add_u32_e32 v149, v40, v42
	v_add_u32_e32 v150, v41, v43
	v_add_u32_e32 v151, v41, v46
	s_mov_b64 s[16:17], 0x40000
	s_mov_b32 s15, s1
	v_mov_b32_e32 v54, 0
	v_mov_b32_e32 v55, v103
	v_mov_b32_e32 v56, v103
	v_mov_b32_e32 v57, v103
	v_mov_b32_e32 v58, 0
	v_mov_b32_e32 v59, v103
	v_mov_b32_e32 v60, v103
	v_mov_b32_e32 v61, v103
	v_mov_b32_e32 v50, 0
	v_mov_b32_e32 v51, v103
	v_mov_b32_e32 v52, v103
	v_mov_b32_e32 v53, v103
	v_mov_b32_e32 v46, 0
	v_mov_b32_e32 v47, v103
	v_mov_b32_e32 v48, v103
	v_mov_b32_e32 v49, v103
	v_mov_b32_e32 v42, 0
	v_mov_b32_e32 v43, v103
	v_mov_b32_e32 v44, v103
	v_mov_b32_e32 v45, v103
	v_mov_b32_e32 v38, 0
	v_mov_b32_e32 v39, v103
	v_mov_b32_e32 v40, v103
	v_mov_b32_e32 v41, v103
	v_mov_b32_e32 v30, 0
	v_mov_b32_e32 v31, v103
	v_mov_b32_e32 v32, v103
	v_mov_b32_e32 v33, v103
	v_mov_b32_e32 v34, 0
	v_mov_b32_e32 v36, v103
	v_mov_b32_e32 v37, v103
	v_readlane_b32 s41, v245, 27
	v_readlane_b32 s42, v245, 28
	v_readlane_b32 s43, v245, 29
	v_readlane_b32 s44, v245, 30
	v_readlane_b32 s45, v245, 31
	v_readlane_b32 s46, v245, 32
	v_readlane_b32 s47, v245, 33
	v_readlane_b32 s50, v245, 36
	v_readlane_b32 s51, v245, 37
	v_readlane_b32 s52, v245, 38
	v_readlane_b32 s53, v245, 39
	v_readlane_b32 s54, v245, 40
	v_readlane_b32 s55, v245, 41
	s_waitcnt vmcnt(18)
	s_mov_b32 s98, 0xaaaaaaaa
	s_mov_b32 s99, 0xaaaaaaaa
	s_mov_b32 s100, 0xcccccccc
	s_mov_b32 s101, 0xcccccccc
	v_mbcnt_lo_u32_b32 v251, -1, 0
	v_mbcnt_hi_u32_b32 v251, -1, v251
	v_and_b32_e32 v252, 12, v251
	v_lshlrev_b32_e32 v252, 4, v252
	v_and_b32_e32 v251, 3, v251
	v_lshl_add_u32 v251, v251, 2, v252
	s_branch .LBB0_1041

.LBB0_1041:
	s_bitcmp1_b32 s15, 0
	s_cselect_b32 s8, 0xf400, 0
	s_add_i32 s8, s8, 0
	v_add_u32_e32 v222, s8, v135
	v_add_u32_e32 v87, v222, v102
	ds_read_b128 v[82:85], v87
	ds_read_b128 v[92:95], v87 offset:64
	v_cvt_pk_bf16_f32 v78, v58, v59
	v_cvt_pk_bf16_f32 v79, v60, v61
	v_cvt_pk_bf16_f32 v80, v54, v55
	v_cvt_pk_bf16_f32 v81, v56, v57
	ds_read_b128 v[166:169], v87 offset:128
	ds_read_b128 v[170:173], v87 offset:192
	v_cvt_pk_bf16_f32 v88, v50, v51
	s_waitcnt lgkmcnt(3)
	v_mfma_f32_16x16x32_bf16 v[82:85], v[82:85], v[78:81], 0
	v_cvt_pk_bf16_f32 v89, v52, v53
	v_cvt_pk_bf16_f32 v90, v46, v47
	v_cvt_pk_bf16_f32 v91, v48, v49
	ds_read_b128 v[174:177], v87 offset:4352
	v_cvt_pk_bf16_f32 v96, v42, v43
	s_waitcnt lgkmcnt(3)
	v_mfma_f32_16x16x32_bf16 v[82:85], v[92:95], v[88:91], v[82:85]
	v_cvt_pk_bf16_f32 v97, v44, v45
	v_cvt_pk_bf16_f32 v98, v38, v39
	v_cvt_pk_bf16_f32 v99, v40, v41
	v_cvt_pk_bf16_f32 v92, v30, v31
	v_cvt_pk_bf16_f32 v93, v32, v33
	s_waitcnt lgkmcnt(2)
	v_mfma_f32_16x16x32_bf16 v[82:85], v[166:169], v[96:99], v[82:85]
	ds_read_b128 v[166:169], v87 offset:4416
	v_cvt_pk_bf16_f32 v94, v34, v35
	v_cvt_pk_bf16_f32 v95, v36, v37
	v_add3_u32 v100, s8, v102, v135
	ds_read_b128 v[178:181], v100 offset:8832
	s_waitcnt lgkmcnt(3)
	v_mfma_f32_16x16x32_bf16 v[82:85], v[170:173], v[92:95], v[82:85]
	v_add_u32_e32 v101, v222, v138
	ds_read_b128 v[182:185], v101 offset:8832
	s_waitcnt vmcnt(22)
	v_mov_b32_e32 v223, v152
	s_waitcnt lgkmcnt(3)
	v_mfma_f32_16x16x32_bf16 v[170:173], v[174:177], v[78:81], 0
	ds_read_b128 v[174:177], v87 offset:4480
	s_waitcnt vmcnt(21)
	v_mov_b32_e32 v224, v153
	s_waitcnt vmcnt(20)
	v_mov_b32_e32 v225, v154
	s_waitcnt lgkmcnt(3)
	v_mfma_f32_16x16x32_bf16 v[166:169], v[166:169], v[88:91], v[170:173]
	s_waitcnt vmcnt(19)
	v_mov_b32_e32 v226, v155
	s_nop 0
	ds_read_b128 v[170:173], v87 offset:4544
	s_waitcnt lgkmcnt(1)
	v_mfma_f32_16x16x32_bf16 v[166:169], v[174:177], v[96:99], v[166:169]
	ds_read_b128 v[174:177], v100 offset:8704
	s_waitcnt lgkmcnt(1)
	v_mfma_f32_16x16x32_bf16 v[166:169], v[170:173], v[92:95], v[166:169]
	ds_read_b128 v[170:173], v100 offset:8768
	s_waitcnt lgkmcnt(1)
	v_mfma_f32_16x16x32_bf16 v[174:177], v[174:177], v[78:81], 0
	s_waitcnt lgkmcnt(0)
	v_mfma_f32_16x16x32_bf16 v[170:173], v[170:173], v[88:91], v[174:177]
	s_nop 5
	ds_read_b128 v[174:177], v100 offset:8896
	v_mfma_f32_16x16x32_bf16 v[170:173], v[178:181], v[96:99], v[170:173]
	ds_read_b128 v[178:181], v101 offset:8704
	s_waitcnt lgkmcnt(1)
	v_mfma_f32_16x16x32_bf16 v[170:173], v[174:177], v[92:95], v[170:173]
	ds_read_b128 v[174:177], v101 offset:8768
	s_waitcnt lgkmcnt(1)
	v_mfma_f32_16x16x32_bf16 v[178:181], v[178:181], v[78:81], 0
	s_waitcnt lgkmcnt(0)
	v_mfma_f32_16x16x32_bf16 v[174:177], v[174:177], v[88:91], v[178:181]
	s_nop 5
	ds_read_b128 v[178:181], v101 offset:8896
	v_mfma_f32_16x16x32_bf16 v[174:177], v[182:185], v[96:99], v[174:177]
	ds_read_b128 v[182:185], v87 offset:17408
	ds_read_b128 v[186:189], v87 offset:17472
	ds_read_b128 v[190:193], v87 offset:17600
	ds_read_b128 v[152:155], v87 offset:21824
	s_waitcnt lgkmcnt(3)
	v_mfma_f32_16x16x32_bf16 v[182:185], v[182:185], v[78:81], 0
	v_mfma_f32_16x16x32_bf16 v[174:177], v[178:181], v[92:95], v[174:177]
	ds_read_b128 v[178:181], v87 offset:17536
	s_waitcnt lgkmcnt(3)
	v_mfma_f32_16x16x32_bf16 v[182:185], v[186:189], v[88:91], v[182:185]
	ds_read_b128 v[186:189], v87 offset:21760
	s_waitcnt lgkmcnt(1)
	v_mfma_f32_16x16x32_bf16 v[178:181], v[178:181], v[96:99], v[182:185]
	s_waitcnt lgkmcnt(0)
	v_mfma_f32_16x16x32_bf16 v[186:189], v[186:189], v[78:81], 0
	v_mfma_f32_16x16x32_bf16 v[178:181], v[190:193], v[92:95], v[178:181]
	s_nop 1
	ds_read_b128 v[182:185], v87 offset:21888
	ds_read_b128 v[190:193], v87 offset:21952
	ds_read_b128 v[194:197], v100 offset:26112
	ds_read_b128 v[198:201], v100 offset:26176
	ds_read_b128 v[202:205], v100 offset:26240
	ds_read_b128 v[206:209], v100 offset:26304
	ds_read_b128 v[210:213], v101 offset:26112
	ds_read_b128 v[214:217], v101 offset:26176
	v_lshlrev_b32_e32 v100, 16, v156
	v_mfma_f32_16x16x32_bf16 v[152:155], v[152:155], v[88:91], v[186:189]
	s_nop 2
	ds_read_b128 v[186:189], v101 offset:26240
	ds_read_b128 v[218:221], v101 offset:26304
	v_and_b32_e32 v101, 0xffff0000, v156
	v_pk_add_f32 v[100:101], v[100:101], v[82:83] neg_lo:[0,1] neg_hi:[0,1]
	v_lshlrev_b32_e32 v82, 16, v157
	v_and_b32_e32 v83, 0xffff0000, v157
	v_pk_add_f32 v[156:157], v[82:83], v[84:85] neg_lo:[0,1] neg_hi:[0,1]
	s_waitcnt lgkmcnt(7)
	v_mfma_f32_16x16x32_bf16 v[82:85], v[194:197], v[78:81], 0
	v_add_u32_e32 v194, v222, v139
	v_lshlrev_b32_e32 v87, 16, v225
	v_sub_f32_e32 v87, v87, v174
	s_waitcnt lgkmcnt(3)
	v_mfma_f32_16x16x32_bf16 v[78:81], v[210:213], v[78:81], 0
	v_mfma_f32_16x16x32_bf16 v[152:155], v[182:185], v[96:99], v[152:155]
	v_lshlrev_b32_e32 v182, 16, v145
	v_and_b32_e32 v183, 0xffff0000, v145
	v_pk_add_f32 v[182:183], v[182:183], v[166:167] neg_lo:[0,1] neg_hi:[0,1]
	v_lshlrev_b32_e32 v166, 16, v147
	v_mfma_f32_16x16x32_bf16 v[82:85], v[198:201], v[88:91], v[82:85]
	v_and_b32_e32 v167, 0xffff0000, v147
	v_pk_add_f32 v[184:185], v[166:167], v[168:169] neg_lo:[0,1] neg_hi:[0,1]
	v_lshlrev_b32_e32 v166, 16, v223
	s_waitcnt lgkmcnt(2)
	v_mfma_f32_16x16x32_bf16 v[78:81], v[214:217], v[88:91], v[78:81]
	v_and_b32_e32 v167, 0xffff0000, v223
	v_and_b32_e32 v145, 0xffff0000, v225
	v_lshlrev_b32_e32 v147, 16, v226
	v_mfma_f32_16x16x32_bf16 v[152:155], v[190:193], v[92:95], v[152:155]
	v_add_f32_e64 v190, v166, -v170
	v_add_f32_e64 v191, v167, -v171
	v_lshlrev_b32_e32 v166, 16, v224
	v_and_b32_e32 v167, 0xffff0000, v224
	v_pk_add_f32 v[192:193], v[166:167], v[172:173] neg_lo:[0,1] neg_hi:[0,1]
	ds_read_b128 v[88:91], v194 offset:37120
	ds_read_b128 v[166:169], v194 offset:34816
	v_mfma_f32_16x16x32_bf16 v[82:85], v[202:205], v[96:99], v[82:85]
	v_cvt_pk_bf16_f32 v172, v182, v183
	v_cvt_pk_bf16_f32 v173, v184, v185
	ds_read_b128 v[182:185], v194 offset:39424
	s_waitcnt lgkmcnt(4)
	v_mfma_f32_16x16x32_bf16 v[78:81], v[186:189], v[96:99], v[78:81]
	v_and_b32_e32 v170, 0xffff0000, v226
	v_sub_f32_e32 v177, v170, v177
	v_cvt_pk_bf16_f32 v170, v100, v101
	v_cvt_pk_bf16_f32 v171, v156, v157
	v_mfma_f32_16x16x32_bf16 v[82:85], v[206:209], v[92:95], v[82:85]
	v_cvt_pk_bf16_f32 v174, v190, v191
	s_nop 0
	s_nop 0
	s_nop 0
	s_nop 0
	s_waitcnt lgkmcnt(3)
	v_mfma_f32_16x16x32_bf16 v[78:81], v[218:221], v[92:95], v[78:81]
	v_sub_f32_e32 v92, v147, v176
	v_sub_f32_e32 v93, v145, v175
	v_cvt_pk_bf16_f32 v175, v192, v193
	s_waitcnt lgkmcnt(1)
	v_mfma_f32_16x16x32_bf16 v[98:101], v[166:169], v[170:173], v[178:181]
	ds_read_b128 v[166:169], v194 offset:39488
	v_cvt_pk_bf16_f32 v176, v87, v93
	v_cvt_pk_bf16_f32 v177, v92, v177
	v_mfma_f32_16x16x32_bf16 v[94:97], v[88:91], v[170:173], v[152:155]
	s_nop 0
	s_nop 0
	s_nop 0
	s_nop 0
	ds_read_b128 v[152:155], v194 offset:41728
	s_waitcnt lgkmcnt(2)
	v_mfma_f32_16x16x32_bf16 v[82:85], v[182:185], v[170:173], v[82:85]
	v_mov_b32_e32 v182, v129
	s_nop 0
	s_nop 0
	v_pk_mul_f32 v[60:61], v[60:61], v[182:183] op_sel_hi:[1,0]
	s_waitcnt lgkmcnt(1)
	v_mfma_f32_16x16x32_bf16 v[90:93], v[166:169], v[174:177], v[82:85]
	s_nop 2
	ds_read_b128 v[82:85], v194 offset:41792
	ds_read_b128 v[166:169], v194 offset:44032
	v_pk_mul_f32 v[58:59], v[58:59], v[182:183] op_sel_hi:[1,0]
	v_pk_mul_f32 v[56:57], v[56:57], v[182:183] op_sel_hi:[1,0]
	s_waitcnt lgkmcnt(2)
	v_mfma_f32_16x16x32_bf16 v[78:81], v[152:155], v[170:173], v[78:81]
	ds_read_b128 v[152:155], v194 offset:44096
	v_pk_mul_f32 v[54:55], v[54:55], v[182:183] op_sel_hi:[1,0]
	v_pk_mul_f32 v[52:53], v[52:53], v[182:183] op_sel_hi:[1,0]
	s_waitcnt lgkmcnt(2)
	v_mfma_f32_16x16x32_bf16 v[86:89], v[82:85], v[174:177], v[78:81]
	ds_read_b128 v[82:85], v194 offset:46400
	v_pk_mul_f32 v[50:51], v[50:51], v[182:183] op_sel_hi:[1,0]
	ds_read_b128 v[162:165], v194 offset:51008
	ds_read_b128 v[78:81], v194 offset:46336
	s_waitcnt lgkmcnt(4)
	v_mfma_f32_16x16x32_bf16 v[58:61], v[166:169], v[170:173], v[58:61]
	v_add3_u32 v168, s8, v139, v135
	v_pk_mul_f32 v[48:49], v[48:49], v[182:183] op_sel_hi:[1,0]
	v_pk_mul_f32 v[46:47], v[46:47], v[182:183] op_sel_hi:[1,0]
	s_waitcnt lgkmcnt(3)
	v_mfma_f32_16x16x32_bf16 v[58:61], v[152:155], v[174:177], v[58:61]
	ds_read_b128 v[152:155], v194 offset:48640
	v_add_u32_e32 v166, v222, v140
	v_pk_mul_f32 v[44:45], v[44:45], v[182:183] op_sel_hi:[1,0]
	s_waitcnt lgkmcnt(1)
	v_mfma_f32_16x16x32_bf16 v[54:57], v[78:81], v[170:173], v[54:57]
	ds_read_b128 v[78:81], v194 offset:48704
	v_pk_mul_f32 v[42:43], v[42:43], v[182:183] op_sel_hi:[1,0]
	ds_read_b128 v[178:181], v168 offset:57856
	v_mfma_f32_16x16x32_bf16 v[54:57], v[82:85], v[174:177], v[54:57]
	ds_read_b128 v[82:85], v194 offset:50944
	v_pk_mul_f32 v[40:41], v[40:41], v[182:183] op_sel_hi:[1,0]
	v_pk_mul_f32 v[38:39], v[38:39], v[182:183] op_sel_hi:[1,0]
	s_waitcnt lgkmcnt(3)
	v_mfma_f32_16x16x32_bf16 v[50:53], v[152:155], v[170:173], v[50:53]
	s_nop 0
	s_nop 0
	s_nop 0
	s_waitcnt lgkmcnt(2)
	v_mfma_f32_16x16x32_bf16 v[50:53], v[78:81], v[174:177], v[50:53]
	ds_read_b128 v[78:81], v168 offset:53248
	s_nop 0
	v_pk_mul_f32 v[32:33], v[32:33], v[182:183] op_sel_hi:[1,0]
	s_waitcnt lgkmcnt(1)
	v_mfma_f32_16x16x32_bf16 v[46:49], v[82:85], v[170:173], v[46:49]
	ds_read_b128 v[82:85], v168 offset:53312
	v_pk_mul_f32 v[30:31], v[30:31], v[182:183] op_sel_hi:[1,0]
	v_pk_mul_f32 v[36:37], v[36:37], v[182:183] op_sel_hi:[1,0]
	v_mfma_f32_16x16x32_bf16 v[46:49], v[162:165], v[174:177], v[46:49]
	ds_read_b128 v[160:163], v166 offset:53248
	ds_read_b128 v[164:167], v166 offset:53312
	v_pk_mul_f32 v[34:35], v[34:35], v[182:183] op_sel_hi:[1,0]
	s_waitcnt lgkmcnt(3)
	v_mfma_f32_16x16x32_bf16 v[42:45], v[78:81], v[170:173], v[42:45]
	s_nop 0
	s_nop 0
	ds_read_b128 v[70:73], v168 offset:57920
	s_waitcnt lgkmcnt(3)
	v_mfma_f32_16x16x32_bf16 v[42:45], v[82:85], v[174:177], v[42:45]
	s_nop 0
	s_nop 0
	ds_read_b128 v[74:77], v168 offset:60160
	s_waitcnt lgkmcnt(3)
	v_mfma_f32_16x16x32_bf16 v[38:41], v[160:163], v[170:173], v[38:41]
	ds_read_b128 v[158:161], v168 offset:60224
	v_mfma_f32_16x16x32_bf16 v[30:33], v[178:181], v[170:173], v[30:33]
	s_waitcnt lgkmcnt(1)
	v_mfma_f32_16x16x32_bf16 v[34:37], v[74:77], v[170:173], v[34:37]
	v_mfma_f32_16x16x32_bf16 v[30:33], v[70:73], v[174:177], v[30:33]
	v_mul_f32_e32 v184, v98, v98
	v_mul_f32_e32 v185, v99, v99
	v_mul_f32_e32 v186, v100, v100
	v_mul_f32_e32 v187, v101, v101
	v_mfma_f32_16x16x32_bf16 v[38:41], v[164:167], v[174:177], v[38:41]
	v_mul_f32_e32 v188, v94, v94
	v_mul_f32_e32 v189, v95, v95
	v_mul_f32_e32 v190, v96, v96
	v_mul_f32_e32 v191, v97, v97
	s_waitcnt lgkmcnt(0)
	v_mfma_f32_16x16x32_bf16 v[34:37], v[158:161], v[174:177], v[34:37]
	v_mul_f32_e32 v192, v90, v90
	v_mul_f32_e32 v193, v91, v91
	v_mul_f32_e32 v194, v92, v92
	v_mul_f32_e32 v195, v93, v93
	v_mul_f32_e32 v196, v86, v86
	v_mul_f32_e32 v197, v87, v87
	v_mul_f32_e32 v198, v88, v88
	v_mul_f32_e32 v199, v89, v89
	v_add_f32_dpp v70, v184, v184 row_ror:8 row_mask:0xf bank_mask:0xf
	v_add_f32_dpp v71, v185, v185 row_ror:8 row_mask:0xf bank_mask:0xf
	v_add_f32_dpp v72, v186, v186 row_ror:8 row_mask:0xf bank_mask:0xf
	v_add_f32_dpp v73, v187, v187 row_ror:8 row_mask:0xf bank_mask:0xf
	v_add_f32_dpp v74, v188, v188 row_ror:8 row_mask:0xf bank_mask:0xf
	v_add_f32_dpp v75, v189, v189 row_ror:8 row_mask:0xf bank_mask:0xf
	v_add_f32_dpp v76, v190, v190 row_ror:8 row_mask:0xf bank_mask:0xf
	v_add_f32_dpp v77, v191, v191 row_ror:8 row_mask:0xf bank_mask:0xf
	v_add_f32_dpp v70, v192, v192 row_ror:8 row_mask:0xf bank_mask:0xc
	v_add_f32_dpp v71, v193, v193 row_ror:8 row_mask:0xf bank_mask:0xc
	v_add_f32_dpp v72, v194, v194 row_ror:8 row_mask:0xf bank_mask:0xc
	v_add_f32_dpp v73, v195, v195 row_ror:8 row_mask:0xf bank_mask:0xc
	v_add_f32_dpp v74, v196, v196 row_ror:8 row_mask:0xf bank_mask:0xc
	v_add_f32_dpp v75, v197, v197 row_ror:8 row_mask:0xf bank_mask:0xc
	v_add_f32_dpp v76, v198, v198 row_ror:8 row_mask:0xf bank_mask:0xc
	v_add_f32_dpp v77, v199, v199 row_ror:8 row_mask:0xf bank_mask:0xc
	v_add_f32_dpp v184, v70, v70 row_half_mirror row_mask:0xf bank_mask:0x5
	v_add_f32_dpp v185, v71, v71 row_half_mirror row_mask:0xf bank_mask:0x5
	v_add_f32_dpp v186, v72, v72 row_half_mirror row_mask:0xf bank_mask:0x5
	v_add_f32_dpp v187, v73, v73 row_half_mirror row_mask:0xf bank_mask:0x5
	v_add_f32_dpp v184, v74, v74 row_half_mirror row_mask:0xf bank_mask:0xa
	v_add_f32_dpp v185, v75, v75 row_half_mirror row_mask:0xf bank_mask:0xa
	v_add_f32_dpp v186, v76, v76 row_half_mirror row_mask:0xf bank_mask:0xa
	v_add_f32_dpp v187, v77, v77 row_half_mirror row_mask:0xf bank_mask:0xa
	v_add_f32_dpp v70, v184, v184 quad_perm:[2,3,0,1] row_mask:0xf bank_mask:0xf
	v_add_f32_dpp v71, v186, v186 quad_perm:[2,3,0,1] row_mask:0xf bank_mask:0xf
	v_add_f32_dpp v72, v185, v185 quad_perm:[2,3,0,1] row_mask:0xf bank_mask:0xf
	v_add_f32_dpp v73, v187, v187 quad_perm:[2,3,0,1] row_mask:0xf bank_mask:0xf
	v_cndmask_b32_e64 v74, v70, v71, s[100:101]
	v_cndmask_b32_e64 v75, v72, v73, s[100:101]
	s_nop 0
	v_add_f32_dpp v76, v74, v74 quad_perm:[1,0,3,2] row_mask:0xf bank_mask:0xf
	v_add_f32_dpp v77, v75, v75 quad_perm:[1,0,3,2] row_mask:0xf bank_mask:0xf
	v_add3_u32 v200, s3, v135, v251
	v_cndmask_b32_e64 v76, v76, v77, s[98:99]
	ds_write_b32 v200, v76
	s_waitcnt lgkmcnt(0)
	s_barrier
	ds_read_b32 v70, v136
	s_waitcnt lgkmcnt(0)
	s_nop 0
	v_add_f32_dpp v70, v70, v70 quad_perm:[1,0,3,2] row_mask:0xf bank_mask:0xf bound_ctrl:1
	s_nop 1
	v_add_f32_dpp v70, v70, v70 quad_perm:[2,3,0,1] row_mask:0xf bank_mask:0xf bound_ctrl:1
	s_nop 1
	v_mov_b32_dpp v71, v70 row_half_mirror row_mask:0xf bank_mask:0xf bound_ctrl:1
	s_and_saveexec_b64 s[18:19], s[6:7]
	s_cbranch_execz .LBB0_1075
	v_add_f32_e32 v70, v70, v71
	v_fmamk_f32 v70, v70, 0x3c000000, v146
	s_mov_b32 s8, 0xf800000
	v_mul_f32_e32 v71, 0x4f800000, v70
	v_cmp_gt_f32_e32 vcc, s8, v70
	s_nop 1
	v_cndmask_b32_e32 v70, v70, v71, vcc
	v_sqrt_f32_e32 v71, v70
	s_nop 0
	v_add_u32_e32 v72, -1, v71
	v_fma_f32 v74, -v72, v71, v70
	v_add_u32_e32 v73, 1, v71
	v_cmp_ge_f32_e64 s[8:9], 0, v74
	s_nop 1
	v_cndmask_b32_e64 v72, v71, v72, s[8:9]
	v_fma_f32 v71, -v73, v71, v70
	v_cmp_lt_f32_e64 s[8:9], 0, v71
	s_nop 1
	v_cndmask_b32_e64 v71, v72, v73, s[8:9]
	v_mul_f32_e32 v72, 0x37800000, v71
	v_cndmask_b32_e32 v71, v71, v72, vcc
	v_cmp_class_f32_e32 vcc, v70, v148
	s_nop 1
	v_cndmask_b32_e32 v70, v71, v70, vcc
	v_div_scale_f32 v71, s[8:9], v70, v70, 1.0
	v_rcp_f32_e32 v72, v71
	s_nop 0
	v_fma_f32 v73, -v71, v72, 1.0
	v_fmac_f32_e32 v72, v73, v72
	v_div_scale_f32 v73, vcc, 1.0, v70, 1.0
	v_mul_f32_e32 v74, v73, v72
	v_fma_f32 v75, -v71, v74, v73
	v_fmac_f32_e32 v74, v75, v72
	v_fma_f32 v71, -v71, v74, v73
	v_div_fmas_f32 v71, v71, v72, v74
	v_div_fixup_f32 v70, v71, v70, 1.0
	ds_write_b32 v137, v70
.LBB0_1075:
	s_or_b64 exec, exec, s[18:19]
	s_add_i32 s8, s15, 1
	s_cmp_eq_u32 s15, 31
	s_cbranch_scc1 .LBB0_1077
	s_bitcmp1_b32 s8, 0
	s_cselect_b32 s9, 0xf400, 0
	s_add_i32 s9, s9, 0
	v_add_u32_e32 v70, s9, v130
	s_waitcnt vmcnt(9)
	ds_write_b128 v70, v[2:5]
	ds_write_b128 v70, v[6:9] offset:17408
	v_add_u32_e32 v70, s9, v131
	v_add_u32_e32 v71, s9, v132
	ds_write_b128 v70, v[10:13] offset:44032
	ds_write_b128 v71, v[14:17]
	ds_write_b128 v71, v[18:21] offset:17408
	v_add_u32_e32 v71, s9, v133
	ds_write_b128 v71, v[22:25] offset:44032
	ds_write_b128 v70, v[26:29] offset:34816
.LBB0_1077:
	s_waitcnt lgkmcnt(0)
	s_barrier
	ds_read_b128 v[70:73], v141
	ds_read_b128 v[74:77], v142
	s_cmp_gt_u32 s15, 29
	s_nop 0
	s_nop 0
	s_waitcnt lgkmcnt(1)
	v_mul_f32_e32 v70, v98, v70
	v_mul_f32_e32 v70, v128, v70
	v_mul_f32_e32 v71, v99, v71
	v_cvt_pk_bf16_f32 v70, v70, s0
	ds_write_b16 v149, v70
	v_mul_f32_e32 v70, v128, v71
	v_cvt_pk_bf16_f32 v70, v70, s0
	ds_write_b16 v149, v70 offset:272
	v_mul_f32_e32 v70, v100, v72
	v_mul_f32_e32 v70, v128, v70
	v_cvt_pk_bf16_f32 v70, v70, s0
	ds_write_b16 v149, v70 offset:544
	v_mul_f32_e32 v70, v101, v73
	v_mul_f32_e32 v70, v128, v70
	v_cvt_pk_bf16_f32 v70, v70, s0
	ds_write_b16 v149, v70 offset:816
	s_waitcnt lgkmcnt(4)
	v_mul_f32_e32 v70, v94, v74
	v_mul_f32_e32 v70, v128, v70
	v_cvt_pk_bf16_f32 v70, v70, s0
	ds_write_b16 v149, v70 offset:4352
	v_mul_f32_e32 v70, v95, v75
	v_mul_f32_e32 v70, v128, v70
	v_cvt_pk_bf16_f32 v70, v70, s0
	ds_write_b16 v149, v70 offset:4624
	v_mul_f32_e32 v70, v96, v76
	v_mul_f32_e32 v70, v128, v70
	v_cvt_pk_bf16_f32 v70, v70, s0
	ds_write_b16 v149, v70 offset:4896
	ds_read_b128 v[70:73], v143
	v_mul_f32_e32 v74, v97, v77
	v_mul_f32_e32 v74, v128, v74
	v_cvt_pk_bf16_f32 v74, v74, s0
	ds_write_b16 v149, v74 offset:5168
	ds_read_b128 v[74:77], v144
	s_waitcnt lgkmcnt(2)
	v_mul_f32_e32 v70, v90, v70
	v_mul_f32_e32 v70, v128, v70
	v_cvt_pk_bf16_f32 v70, v70, s0
	ds_write_b16 v149, v70 offset:8704
	v_mul_f32_e32 v70, v91, v71
	v_mul_f32_e32 v70, v128, v70
	v_cvt_pk_bf16_f32 v70, v70, s0
	ds_write_b16 v149, v70 offset:8976
	v_mul_f32_e32 v70, v92, v72
	v_mul_f32_e32 v70, v128, v70
	v_cvt_pk_bf16_f32 v70, v70, s0
	ds_write_b16 v149, v70 offset:9248
	v_mul_f32_e32 v70, v93, v73
	v_mul_f32_e32 v70, v128, v70
	v_cvt_pk_bf16_f32 v70, v70, s0
	ds_write_b16 v149, v70 offset:9520
	s_waitcnt lgkmcnt(4)
	v_mul_f32_e32 v70, v86, v74
	v_mul_f32_e32 v70, v128, v70
	v_cvt_pk_bf16_f32 v70, v70, s0
	ds_write_b16 v149, v70 offset:13056
	v_mul_f32_e32 v70, v87, v75
	v_mul_f32_e32 v70, v128, v70
	v_cvt_pk_bf16_f32 v70, v70, s0
	ds_write_b16 v149, v70 offset:13328
	v_mul_f32_e32 v70, v88, v76
	v_mul_f32_e32 v70, v128, v70
	v_cvt_pk_bf16_f32 v70, v70, s0
	ds_write_b16 v149, v70 offset:13600
	v_mul_f32_e32 v70, v89, v77
	v_mul_f32_e32 v70, v128, v70
	v_cvt_pk_bf16_f32 v70, v70, s0
	ds_write_b16 v149, v70 offset:13872
	s_waitcnt lgkmcnt(0)
	s_barrier
	ds_read_b128 v[70:73], v150
	ds_read_b128 v[74:77], v151
	v_lshlrev_b32_e32 v88, 16, v66
	v_and_b32_e32 v89, 0xffff0000, v66
	s_nop 0
	s_waitcnt lgkmcnt(1)
	v_lshlrev_b32_e32 v86, 16, v70
	v_and_b32_e32 v87, 0xffff0000, v70
	v_pk_mul_f32 v[86:87], v[88:89], v[86:87]
	v_lshlrev_b32_e32 v70, 16, v71
	v_cvt_pk_bf16_f32 v66, v86, v87
	v_and_b32_e32 v71, 0xffff0000, v71
	v_lshlrev_b32_e32 v86, 16, v67
	v_and_b32_e32 v87, 0xffff0000, v67
	v_pk_mul_f32 v[70:71], v[86:87], v[70:71]
	v_lshlrev_b32_e32 v86, 16, v68
	v_cvt_pk_bf16_f32 v67, v70, v71
	v_lshlrev_b32_e32 v70, 16, v72
	v_and_b32_e32 v71, 0xffff0000, v72
	v_and_b32_e32 v87, 0xffff0000, v68
	v_pk_mul_f32 v[70:71], v[86:87], v[70:71]
	v_lshlrev_b32_e32 v72, 16, v69
	v_cvt_pk_bf16_f32 v68, v70, v71
	v_lshlrev_b32_e32 v70, 16, v73
	v_and_b32_e32 v71, 0xffff0000, v73
	v_and_b32_e32 v73, 0xffff0000, v69
	v_pk_mul_f32 v[70:71], v[72:73], v[70:71]
	s_nop 0
	v_cvt_pk_bf16_f32 v69, v70, v71
	global_store_dwordx4 v[126:127], v[66:69], off
	s_nop 0
	s_nop 0
	s_waitcnt lgkmcnt(0)
	v_lshlrev_b32_e32 v66, 16, v74
	v_and_b32_e32 v67, 0xffff0000, v74
	v_lshlrev_b32_e32 v68, 16, v62
	v_and_b32_e32 v69, 0xffff0000, v62
	v_pk_mul_f32 v[66:67], v[68:69], v[66:67]
	v_lshlrev_b32_e32 v68, 16, v63
	v_cvt_pk_bf16_f32 v62, v66, v67
	v_lshlrev_b32_e32 v66, 16, v75
	v_and_b32_e32 v67, 0xffff0000, v75
	v_and_b32_e32 v69, 0xffff0000, v63
	v_pk_mul_f32 v[66:67], v[68:69], v[66:67]
	v_lshlrev_b32_e32 v68, 16, v64
	v_cvt_pk_bf16_f32 v63, v66, v67
	v_lshlrev_b32_e32 v66, 16, v76
	v_and_b32_e32 v67, 0xffff0000, v76
	v_and_b32_e32 v69, 0xffff0000, v64
	v_pk_mul_f32 v[66:67], v[68:69], v[66:67]
	v_lshlrev_b32_e32 v68, 16, v65
	v_cvt_pk_bf16_f32 v64, v66, v67
	v_lshlrev_b32_e32 v66, 16, v77
	v_and_b32_e32 v67, 0xffff0000, v77
	v_and_b32_e32 v69, 0xffff0000, v65
	v_pk_mul_f32 v[66:67], v[68:69], v[66:67]
	s_nop 0
	v_cvt_pk_bf16_f32 v65, v66, v67
	s_nop 0
	s_nop 0
	s_nop 0
	s_nop 0
	s_nop 0
	s_nop 0
	global_store_dwordx4 v[124:125], v[62:65], off
	s_waitcnt vmcnt(2)
	v_mov_b32_e32 v129, v250
	v_mov_b32_e32 v156, v230
	v_mov_b32_e32 v157, v231
	v_mov_b32_e32 v145, v232
	v_mov_b32_e32 v147, v233
	v_mov_b32_e32 v152, v234
	v_mov_b32_e32 v153, v235
	v_mov_b32_e32 v154, v236
	v_mov_b32_e32 v155, v237
	v_mov_b64_e32 v[78:79], v[238:239]
	v_mov_b64_e32 v[80:81], v[240:241]
	v_mov_b64_e32 v[82:83], v[246:247]
	v_mov_b64_e32 v[84:85], v[248:249]
	s_cbranch_scc1 .LBB0_1040
	s_add_i32 s18, s20, s15
	s_ashr_i32 s15, s14, 31
	v_lshl_add_u64 v[2:3], s[14:15], 0, v[108:109]
	v_lshlrev_b64 v[14:15], 11, v[2:3]
	v_lshl_add_u64 v[2:3], v[104:105], 0, v[14:15]
	v_lshl_add_u64 v[6:7], v[106:107], 0, v[14:15]
	v_lshl_add_u64 v[14:15], v[116:117], 0, v[14:15]
	s_ashr_i32 s19, s18, 31
	global_load_dwordx4 v[238:241], v[14:15], off nt
	v_lshl_add_u64 v[14:15], s[14:15], 0, v[112:113]
	s_lshl_b64 s[22:23], s[18:19], 14
	v_lshlrev_b64 v[26:27], 11, v[14:15]
	v_lshl_add_u64 v[22:23], v[118:119], 0, s[22:23]
	v_lshl_add_u64 v[14:15], v[104:105], 0, v[26:27]
	v_lshl_add_u64 v[18:19], v[106:107], 0, v[26:27]
	v_lshl_add_u64 v[26:27], v[116:117], 0, v[26:27]
	s_lshl_b64 s[18:19], s[18:19], 13
	v_lshl_add_u64 v[62:63], v[122:123], 0, s[22:23]
	v_lshl_add_u64 v[10:11], v[110:111], 1, v[22:23]
	v_lshl_add_u64 v[22:23], v[114:115], 1, v[22:23]
	global_load_dwordx4 v[246:249], v[26:27], off nt
	v_lshl_add_u64 v[26:27], v[120:121], 0, s[18:19]
	v_lshl_add_u64 v[64:65], s[0:1], 2, v[62:63]
	v_lshl_add_u64 v[62:63], s[10:11], 2, v[62:63]
	global_load_dwordx4 v[2:5], v[2:3], off nt
	s_nop 0
	global_load_dwordx4 v[6:9], v[6:7], off nt
	s_nop 0
	global_load_dwordx4 v[10:13], v[10:11], off nt
	s_nop 0
	global_load_dwordx4 v[14:17], v[14:15], off nt
	s_nop 0
	global_load_dwordx4 v[18:21], v[18:19], off nt
	s_nop 0
	global_load_dwordx4 v[22:25], v[22:23], off nt
	s_nop 0
	global_load_dwordx4 v[26:29], v[26:27], off nt
	s_nop 0
	global_load_dword v230, v[64:65], off nt
	global_load_dword v231, v[62:63], off offset:256 nt
	global_load_dword v232, v[62:63], off offset:512 nt
	global_load_dword v233, v[62:63], off offset:768 nt
	global_load_dword v234, v[62:63], off offset:1024 nt
	global_load_dword v235, v[62:63], off offset:1280 nt
	global_load_dword v236, v[62:63], off offset:1536 nt
	global_load_dword v237, v[62:63], off offset:1792 nt
	global_load_dword v250, v103, s[12:13]
	s_branch .LBB0_1040

.LBB0_1178:
	s_sub_i32 s0, s14, s41
	s_addk_i32 s0, 0xff80
	v_readfirstlane_b32 s1, v0
	s_ashr_i32 s6, s0, 1
	s_lshl_b32 s0, s14, 2
	s_and_b32 s0, s0, 4
	s_lshr_b32 s46, s1, 7
	s_lshr_b32 s45, s1, 6
	s_add_i32 s46, s46, s0
	s_mul_i32 s0, s45, 0x2840
	s_and_b32 s42, s1, 64
	s_lshl_b32 s43, s46, 7
	v_mov_b32_e32 v130, v0
	s_add_i32 s44, s0, 0
	s_or_b32 s0, s43, s42
	s_addk_i32 s0, 0x800
	v_and_b32_e32 v131, 63, v130
	v_readlane_b32 s12, v245, 6
	s_lshl_b32 s47, s6, 3
	s_waitcnt vmcnt(24)
	v_lshlrev_b32_e32 v37, 1, v131
	v_or_b32_e32 v4, s0, v131
	s_mul_i32 s0, s6, 0x9000
	v_readlane_b32 s18, v245, 12
	v_or_b32_e32 v162, s43, v37
	s_mul_hi_i32 s1, s6, 0x9000
	v_readlane_b32 s19, v245, 13
	s_add_u32 s0, s18, s0
	s_addc_u32 s1, s19, s1
	v_lshlrev_b64 v[2:3], 2, v[162:163]
	v_lshl_add_u64 v[6:7], s[0:1], 0, v[2:3]
	s_barrier
	global_load_dwordx2 v[28:29], v[6:7], off
	v_add_co_u32_e32 v6, vcc, s76, v6
	v_mov_b32_e32 v5, v163
	s_nop 0
	v_addc_co_u32_e32 v7, vcc, 0, v7, vcc
	global_load_dwordx2 v[26:27], v[6:7], off
	v_lshlrev_b64 v[6:7], 2, v[4:5]
	s_add_u32 s4, s0, 0x3000
	v_lshl_add_u64 v[8:9], s[0:1], 0, v[6:7]
	s_addc_u32 s5, s1, 0
	global_load_dword v58, v[8:9], off
	v_lshl_add_u64 v[8:9], s[4:5], 0, v[2:3]
	global_load_dwordx2 v[24:25], v[8:9], off
	v_add_co_u32_e32 v8, vcc, s76, v8
	s_add_u32 s0, s0, 0x6000
	s_nop 0
	v_addc_co_u32_e32 v9, vcc, 0, v9, vcc
	global_load_dwordx2 v[22:23], v[8:9], off
	v_lshl_add_u64 v[8:9], s[4:5], 0, v[6:7]
	s_addc_u32 s1, s1, 0
	global_load_dword v56, v[8:9], off
	v_lshl_add_u64 v[8:9], s[0:1], 0, v[2:3]
	global_load_dwordx2 v[20:21], v[8:9], off
	v_add_co_u32_e32 v8, vcc, s76, v8
	v_readlane_b32 s26, v245, 20
	s_nop 0
	v_addc_co_u32_e32 v9, vcc, 0, v9, vcc
	v_readlane_b32 s27, v245, 21
	global_load_dwordx2 v[18:19], v[8:9], off
	v_lshl_add_u64 v[8:9], s[0:1], 0, v[6:7]
	s_mul_i32 s0, s6, 0xc000
	s_add_i32 s26, s47, 0x4000
	s_ashr_i32 s27, s26, 31
	s_add_i32 s1, s0, 0x6000000
	s_mul_hi_i32 s5, s26, 0x1800
	s_add_u32 s4, s82, s1
	s_addc_u32 s5, s83, s5
	v_lshlrev_b32_e32 v10, 1, v162
	global_load_dword v57, v[8:9], off
	s_nop 0
	global_load_dword v8, v10, s[4:5]
	global_load_dword v9, v10, s[4:5] offset:2048
	v_lshlrev_b64 v[4:5], 1, v[4:5]
	v_readlane_b32 s24, v245, 18
	s_add_i32 s24, s47, 0x4001
	v_readlane_b32 s22, v245, 16
	s_mul_hi_i32 s1, s24, 0x1800
	v_readlane_b32 s20, v245, 14
	v_readlane_b32 s16, v245, 10
	v_readlane_b32 s56, v245, 26
	v_readlane_b32 s14, v245, 8
	v_readlane_b32 s58, v245, 28
	v_readlane_b32 s59, v245, 29
	v_mov_b32_e32 v67, v163
	v_readlane_b32 s60, v245, 30
	v_lshl_add_u64 v[14:15], s[58:59], 0, v[2:3]
	v_add_co_u32_e32 v2, vcc, s76, v14
	v_lshl_add_u64 v[64:65], s[58:59], 0, v[6:7]
	s_nop 0
	v_addc_co_u32_e32 v3, vcc, 0, v15, vcc
	v_add_co_u32_e32 v6, vcc, s96, v14
	v_readlane_b32 s61, v245, 31
	s_nop 0
	v_addc_co_u32_e32 v7, vcc, 0, v15, vcc
	v_readlane_b32 s62, v245, 32
	v_mov_b32_e32 v68, v163
	v_readlane_b32 s63, v245, 33
	v_readlane_b32 s13, v245, 7
	v_readlane_b32 s15, v245, 9
	v_readlane_b32 s17, v245, 11
	v_readlane_b32 s21, v245, 15
	v_readlane_b32 s23, v245, 17
	v_readlane_b32 s25, v245, 19
	v_readlane_b32 s57, v245, 27
	v_readlane_b32 s64, v245, 34
	v_readlane_b32 s65, v245, 35
	v_readlane_b32 s66, v245, 36
	v_readlane_b32 s67, v245, 37
	v_readlane_b32 s68, v245, 38
	v_readlane_b32 s69, v245, 39
	v_readlane_b32 s70, v245, 40
	v_readlane_b32 s71, v245, 41
	s_waitcnt vmcnt(1)
	v_lshlrev_b32_e32 v51, 16, v8
	v_and_b32_e32 v48, 0xffff0000, v8
	s_waitcnt vmcnt(0)
	v_lshlrev_b32_e32 v50, 16, v9
	v_and_b32_e32 v47, 0xffff0000, v9
	v_lshl_add_u64 v[8:9], s[4:5], 0, v[4:5]
	global_load_ushort v8, v[8:9], off
	s_mul_i32 s4, s24, 0x1800
	s_add_u32 s4, s82, s4
	s_addc_u32 s5, s83, s1
	s_add_i32 s22, s47, 0x4002
	s_add_i32 s1, s0, 0x6003000
	global_load_dword v63, v10, s[4:5]
	global_load_dword v62, v10, s[4:5] offset:2048
	s_waitcnt vmcnt(2)
	v_lshlrev_b32_e32 v49, 16, v8
	v_lshl_add_u64 v[8:9], s[4:5], 0, v[4:5]
	s_mul_hi_i32 s5, s22, 0x1800
	s_add_u32 s4, s82, s1
	s_addc_u32 s5, s83, s5
	s_add_i32 s20, s47, 0x4003
	s_add_i32 s1, s0, 0x6004800
	global_load_ushort v59, v[8:9], off
	global_load_dword v55, v10, s[4:5]
	global_load_dword v61, v10, s[4:5] offset:2048
	v_lshl_add_u64 v[8:9], s[4:5], 0, v[4:5]
	s_mul_hi_i32 s5, s20, 0x1800
	s_add_u32 s4, s82, s1
	s_addc_u32 s5, s83, s5
	s_add_i32 s18, s47, 0x4004
	s_add_i32 s1, s0, 0x6006000
	global_load_ushort v60, v[8:9], off
	global_load_dword v54, v10, s[4:5]
	global_load_dword v53, v10, s[4:5] offset:2048
	v_lshl_add_u64 v[8:9], s[4:5], 0, v[4:5]
	s_mul_hi_i32 s5, s18, 0x1800
	s_add_u32 s4, s82, s1
	s_addc_u32 s5, s83, s5
	s_add_i32 s16, s47, 0x4005
	s_add_i32 s1, s0, 0x6007800
	global_load_ushort v52, v[8:9], off
	global_load_dword v46, v10, s[4:5]
	global_load_dword v45, v10, s[4:5] offset:2048
	v_lshl_add_u64 v[8:9], s[4:5], 0, v[4:5]
	s_mul_hi_i32 s5, s16, 0x1800
	s_add_u32 s4, s82, s1
	s_addc_u32 s5, s83, s5
	s_add_i32 s14, s47, 0x4006
	s_add_i32 s1, s0, 0x6009000
	global_load_ushort v44, v[8:9], off
	global_load_dword v43, v10, s[4:5]
	global_load_dword v42, v10, s[4:5] offset:2048
	v_lshl_add_u64 v[8:9], s[4:5], 0, v[4:5]
	s_mul_hi_i32 s5, s14, 0x1800
	s_add_u32 s4, s82, s1
	s_addc_u32 s5, s83, s5
	s_add_i32 s12, s47, 0x4007
	s_add_i32 s0, s0, 0x600a800
	s_mul_hi_i32 s1, s12, 0x1800
	s_add_u32 s0, s82, s0
	global_load_ushort v41, v[8:9], off
	v_lshl_add_u64 v[8:9], s[4:5], 0, v[4:5]
	s_addc_u32 s1, s83, s1
	global_load_dword v40, v10, s[4:5]
	global_load_dword v39, v10, s[4:5] offset:2048
	global_load_ushort v38, v[8:9], off
	global_load_dword v32, v10, s[0:1]
	global_load_dword v31, v10, s[0:1] offset:2048
	v_add_co_u32_e32 v10, vcc, s97, v64
	v_lshl_add_u64 v[4:5], s[0:1], 0, v[4:5]
	s_nop 0
	v_addc_co_u32_e32 v11, vcc, 0, v65, vcc
	global_load_ushort v30, v[4:5], off
	global_load_dword v33, v[64:65], off
	s_lshl_b32 s0, s46, 2
	global_load_dwordx2 v[4:5], v[14:15], off
	s_add_u32 s48, s86, s0
	global_load_dwordx2 v[2:3], v[2:3], off
	s_nop 0
	global_load_dwordx2 v[8:9], v[6:7], off offset:-4096
	s_nop 0
	global_load_dwordx2 v[6:7], v[6:7], off
	s_addc_u32 s49, s87, 0
	global_load_dword v34, v[10:11], off
	v_add_co_u32_e32 v10, vcc, s85, v14
	s_add_u32 s28, s60, s0
	s_nop 0
	v_addc_co_u32_e32 v11, vcc, 0, v15, vcc
	v_add_co_u32_e32 v16, vcc, s84, v64
	global_load_dwordx2 v[12:13], v[10:11], off offset:-4096
	s_nop 0
	global_load_dwordx2 v[10:11], v[10:11], off
	v_addc_co_u32_e32 v17, vcc, 0, v65, vcc
	global_load_dword v35, v[16:17], off
	v_add_co_u32_e32 v16, vcc, s80, v14
	s_addc_u32 s29, s61, 0
	s_nop 0
	v_addc_co_u32_e32 v17, vcc, 0, v15, vcc
	global_load_dwordx2 v[14:15], v[16:17], off offset:-4096
	s_nop 0
	global_load_dwordx2 v[16:17], v[16:17], off
	v_add_co_u32_e32 v64, vcc, s75, v64
	s_add_u32 s6, s62, s0
	s_nop 0
	v_addc_co_u32_e32 v65, vcc, 0, v65, vcc
	global_load_dword v36, v[64:65], off
	v_and_b32_e32 v64, 0x7c, v37
	v_lshl_add_u32 v37, v131, 2, s44
	v_cmp_eq_u32_e64 s[4:5], 0, v131
	s_addc_u32 s7, s63, 0
	s_waitcnt vmcnt(8)
	v_mul_f32_e32 v65, v24, v8
	v_fmac_f32_e32 v65, v28, v4
	s_waitcnt vmcnt(6)
	v_mul_f32_e32 v66, v56, v34
	v_fmac_f32_e32 v66, v58, v33
	s_waitcnt vmcnt(5)
	v_fmac_f32_e32 v65, v20, v12
	s_waitcnt vmcnt(3)
	v_fmac_f32_e32 v66, v57, v35
	s_waitcnt vmcnt(2)
	v_fmac_f32_e32 v65, v14, v51
	v_mul_f32_e32 v28, 0xbfb8aa3b, v65
	v_exp_f32_e32 v28, v28
	s_waitcnt vmcnt(0)
	v_fmac_f32_e32 v66, v36, v49
	v_add_f32_e32 v28, 1.0, v28
	v_rcp_f32_e32 v28, v28
	s_nop 0
	v_mul_f32_e32 v65, v65, v28
	v_mul_f32_e32 v28, v22, v6
	v_fmac_f32_e32 v28, v26, v2
	v_fmac_f32_e32 v28, v18, v10
	v_fmac_f32_e32 v28, v16, v50
	v_mul_f32_e32 v26, 0xbfb8aa3b, v28
	v_exp_f32_e32 v26, v26
	s_nop 0
	v_add_f32_e32 v26, 1.0, v26
	v_rcp_f32_e32 v26, v26
	s_nop 0
	v_mul_f32_e32 v26, v28, v26
	v_mul_f32_e32 v28, v25, v9
	v_fmac_f32_e32 v28, v29, v5
	v_fmac_f32_e32 v28, v21, v13
	v_fmac_f32_e32 v28, v15, v48
	v_mul_f32_e32 v29, 0xbfb8aa3b, v28
	v_exp_f32_e32 v29, v29
	s_nop 0
	v_add_f32_e32 v29, 1.0, v29
	v_rcp_f32_e32 v29, v29
	s_nop 0
	v_mul_f32_e32 v29, v28, v29
	v_mul_f32_e32 v28, v23, v7
	v_fmac_f32_e32 v28, v27, v3
	v_fmac_f32_e32 v28, v19, v11
	v_fmac_f32_e32 v28, v17, v47
	v_mul_f32_e32 v27, 0xbfb8aa3b, v28
	v_exp_f32_e32 v27, v27
	s_nop 0
	v_add_f32_e32 v27, 1.0, v27
	v_rcp_f32_e32 v27, v27
	s_nop 0
	v_mul_f32_e32 v27, v28, v27
	v_mul_f32_e32 v28, 0xbfb8aa3b, v66
	v_exp_f32_e32 v28, v28
	s_nop 0
	v_add_f32_e32 v28, 1.0, v28
	v_rcp_f32_e32 v58, v28
	v_mul_f32_e32 v28, v29, v29
	v_fmac_f32_e32 v28, v65, v65
	s_nop 1
	v_add_f32_dpp v28, v28, v28 row_ror:8 row_mask:0xf bank_mask:0xf bound_ctrl:1
	s_nop 1
	v_add_f32_dpp v28, v28, v28 row_ror:4 row_mask:0xf bank_mask:0xf bound_ctrl:1
	s_nop 1
	v_add_f32_dpp v28, v28, v28 quad_perm:[2,3,0,1] row_mask:0xf bank_mask:0xf bound_ctrl:1
	s_nop 1
	v_add_f32_dpp v28, v28, v28 quad_perm:[1,0,3,2] row_mask:0xf bank_mask:0xf bound_ctrl:1
	s_nop 1
	v_mov_b32_dpp v67, v28 row_bcast:15 row_mask:0xa bank_mask:0xf
	v_add_f32_e32 v28, v28, v67
	v_mov_b32_e32 v67, v163
	s_nop 1
	v_mov_b32_dpp v67, v28 row_bcast:31 row_mask:0xc bank_mask:0xf
	v_add_f32_e32 v28, v28, v67
	s_nop 0
	v_readlane_b32 s0, v28, 63
	s_nop 1
	v_add_f32_e32 v28, s0, v171
	v_rsq_f32_e32 v28, v28
	s_nop 0
	v_mul_f32_e32 v67, 0x3db504f3, v28
	v_mul_f32_e32 v28, v27, v27
	v_fmac_f32_e32 v28, v26, v26
	s_nop 1
	v_add_f32_dpp v28, v28, v28 row_ror:8 row_mask:0xf bank_mask:0xf bound_ctrl:1
	s_nop 1
	v_add_f32_dpp v28, v28, v28 row_ror:4 row_mask:0xf bank_mask:0xf bound_ctrl:1
	s_nop 1
	v_add_f32_dpp v28, v28, v28 quad_perm:[2,3,0,1] row_mask:0xf bank_mask:0xf bound_ctrl:1
	s_nop 1
	v_add_f32_dpp v28, v28, v28 quad_perm:[1,0,3,2] row_mask:0xf bank_mask:0xf bound_ctrl:1
	s_nop 1
	v_mov_b32_dpp v68, v28 row_bcast:15 row_mask:0xa bank_mask:0xf
	v_add_f32_e32 v28, v28, v68
	v_mov_b32_e32 v68, v163
	s_nop 1
	v_mov_b32_dpp v68, v28 row_bcast:31 row_mask:0xc bank_mask:0xf
	v_add_f32_e32 v28, v28, v68
	s_nop 0
	v_readlane_b32 s0, v28, 63
	s_nop 1
	v_add_f32_e32 v28, s0, v171
	v_rsq_f32_e32 v68, v28
	v_lshlrev_b32_e32 v28, 8, v130
	v_and_b32_e32 v28, 0x100, v28
	v_add3_u32 v28, s44, v64, v28
	v_mul_f32_e32 v26, v26, v68
	v_mul_f32_e32 v27, v27, v68
	v_mul_f32_e32 v64, v65, v67
	ds_write2_b32 v28, v26, v27 offset1:32
	v_mul_f32_e32 v26, v29, v67
	ds_write2_b32 v28, v64, v26 offset0:128 offset1:160
	v_mul_f32_e32 v26, v66, v58
	ds_write_b32 v37, v26 offset:8192
	s_mov_b64 s[0:1], exec
	s_mov_b64 exec, 0xff
	s_cbranch_execz .LBB0_1180
	s_lshl_b64 s[30:31], s[26:27], 6
	s_add_u32 s30, s48, s30
	s_addc_u32 s31, s49, s31
	v_mbcnt_lo_u32_b32 v230, -1, 0
	v_lshlrev_b32_e32 v230, 6, v230
	global_load_dword v26, v230, s[30:31]
	global_load_dword v231, v163, s[28:29]
	global_load_dword v232, v230, s[30:31] offset:32
	global_load_dword v233, v163, s[6:7]
	s_waitcnt vmcnt(0)
	v_mul_f32_e32 v27, 0xbfb8aa3b, v26
	v_fma_f32 v29, v26, s81, -v27
	v_rndne_f32_e32 v58, v27
	v_fmac_f32_e32 v29, 0xb2a5705f, v26
	v_sub_f32_e32 v27, v27, v58
	v_add_f32_e32 v27, v27, v29
	v_exp_f32_e32 v27, v27
	v_cvt_i32_f32_e32 v29, v58
	v_cmp_nlt_f32_e32 vcc, s3, v26
	v_ldexp_f32 v27, v27, v29
	s_nop 0
	v_cndmask_b32_e32 v27, 0, v27, vcc
	v_cmp_ngt_f32_e32 vcc, s2, v26
	s_nop 1
	v_cndmask_b32_e32 v26, v179, v27, vcc
	v_add_f32_e32 v26, 1.0, v26
	v_div_scale_f32 v27, s[50:51], v26, v26, 1.0
	v_rcp_f32_e32 v29, v27
	s_nop 0
	v_fma_f32 v58, -v27, v29, 1.0
	v_fmac_f32_e32 v29, v58, v29
	v_div_scale_f32 v58, vcc, 1.0, v26, 1.0
	v_mul_f32_e32 v64, v58, v29
	v_fma_f32 v65, -v27, v64, v58
	v_fmac_f32_e32 v64, v65, v29
	v_fma_f32 v27, -v27, v64, v58
	v_div_fmas_f32 v27, v27, v29, v64
	v_div_fixup_f32 v26, v27, v26, 1.0
	v_mov_b32_e32 v27, v231
	s_waitcnt vmcnt(0)
	v_mul_f32_e32 v29, 0x3fb8aa3b, v27
	v_fma_f32 v58, v27, s38, -v29
	v_rndne_f32_e32 v64, v29
	v_fmac_f32_e32 v58, 0x32a5705f, v27
	v_sub_f32_e32 v29, v29, v64
	v_add_f32_e32 v29, v29, v58
	v_exp_f32_e32 v29, v29
	v_cvt_i32_f32_e32 v58, v64
	v_cmp_ngt_f32_e32 vcc, s39, v27
	v_ldexp_f32 v29, v29, v58
	s_nop 0
	v_cndmask_b32_e32 v29, 0, v29, vcc
	v_cmp_nlt_f32_e32 vcc, s78, v27
	s_nop 1
	v_cndmask_b32_e32 v27, v179, v29, vcc
	v_mov_b32_e32 v29, v232
	v_mov_b32_e32 v58, v233
	s_waitcnt vmcnt(0)
	v_add_f32_e32 v58, v29, v58
	v_mul_f32_e64 v64, |v58|, s81
	v_fma_f32 v65, |v58|, s81, -v64
	v_rndne_f32_e32 v66, v64
	v_fma_f32 v65, |v58|, s33, v65
	v_sub_f32_e32 v64, v64, v66
	v_add_f32_e32 v64, v64, v65
	v_exp_f32_e32 v64, v64
	v_cvt_i32_f32_e32 v65, v66
	v_cmp_ngt_f32_e64 vcc, |v58|, s3
	v_max_f32_e32 v29, 0, v58
	v_ldexp_f32 v64, v64, v65
	v_cndmask_b32_e32 v64, 0, v64, vcc
	v_cmp_nlt_f32_e64 vcc, |v58|, s2
	s_nop 1
	v_cndmask_b32_e32 v58, v179, v64, vcc
	v_add_f32_e32 v66, 1.0, v58
	v_add_f32_e32 v64, -1.0, v66
	v_sub_f32_e32 v65, v64, v66
	v_add_f32_e32 v65, 1.0, v65
	v_sub_f32_e32 v64, v58, v64
	v_add_f32_e32 v67, v64, v65
	v_frexp_mant_f32_e32 v64, v66
	v_cmp_gt_f32_e32 vcc, s79, v64
	v_cvt_f64_f32_e32 v[64:65], v66
	v_frexp_exp_i32_f64_e32 v64, v[64:65]
	v_subbrev_co_u32_e32 v64, vcc, 0, v64, vcc
	v_sub_u32_e32 v65, 0, v64
	v_ldexp_f32 v66, v66, v65
	v_ldexp_f32 v65, v67, v65
	v_add_f32_e32 v67, -1.0, v66
	v_add_f32_e32 v68, 1.0, v67
	v_sub_f32_e32 v68, v66, v68
	v_add_f32_e32 v68, v65, v68
	v_add_f32_e32 v69, v67, v68
	v_sub_f32_e32 v67, v67, v69
	v_add_f32_e32 v67, v68, v67
	v_add_f32_e32 v68, 1.0, v66
	v_add_f32_e32 v70, -1.0, v68
	v_sub_f32_e32 v66, v66, v70
	v_add_f32_e32 v65, v65, v66
	v_add_f32_e32 v66, v68, v65
	v_sub_f32_e32 v68, v68, v66
	v_add_f32_e32 v65, v65, v68
	v_rcp_f32_e32 v68, v66
	v_cvt_f32_i32_e32 v64, v64
	v_cmp_neq_f32_e32 vcc, s34, v58
	v_mul_f32_e32 v70, v69, v68
	v_mul_f32_e32 v71, v66, v70
	v_fma_f32 v72, v70, v66, -v71
	v_fmac_f32_e32 v72, v70, v65
	v_add_f32_e32 v73, v71, v72
	v_sub_f32_e32 v74, v69, v73
	v_sub_f32_e32 v69, v69, v74
	v_sub_f32_e32 v71, v73, v71
	v_sub_f32_e32 v69, v69, v73
	v_add_f32_e32 v67, v67, v69
	v_sub_f32_e32 v69, v71, v72
	v_add_f32_e32 v67, v69, v67
	v_add_f32_e32 v69, v74, v67
	v_mul_f32_e32 v71, v68, v69
	v_mul_f32_e32 v72, v66, v71
	v_fma_f32 v66, v71, v66, -v72
	v_fmac_f32_e32 v66, v71, v65
	v_sub_f32_e32 v65, v74, v69
	v_add_f32_e32 v65, v67, v65
	v_add_f32_e32 v67, v72, v66
	v_sub_f32_e32 v73, v69, v67
	v_sub_f32_e32 v69, v69, v73
	v_sub_f32_e32 v72, v67, v72
	v_sub_f32_e32 v67, v69, v67
	v_add_f32_e32 v65, v65, v67
	v_sub_f32_e32 v66, v72, v66
	v_add_f32_e32 v65, v66, v65
	v_add_f32_e32 v66, v70, v71
	v_add_f32_e32 v65, v73, v65
	v_sub_f32_e32 v67, v66, v70
	v_mul_f32_e32 v65, v68, v65
	v_sub_f32_e32 v67, v71, v67
	v_add_f32_e32 v65, v67, v65
	v_mul_f32_e32 v70, 0x3f317218, v64
	v_add_f32_e32 v67, v66, v65
	v_fma_f32 v71, v64, s8, -v70
	v_mul_f32_e32 v68, v67, v67
	v_fmac_f32_e32 v71, 0xb102e308, v64
	v_sub_f32_e32 v64, v67, v66
	v_fmamk_f32 v69, v68, 0x3e9b6dac, v169
	v_sub_f32_e32 v64, v65, v64
	v_add_f32_e32 v65, v70, v71
	v_fmaak_f32 v69, v68, v69, 0x3f2aaada
	v_sub_f32_e32 v66, v65, v70
	v_ldexp_f32 v70, v67, 1
	v_mul_f32_e32 v67, v67, v68
	v_mul_f32_e32 v67, v67, v69
	v_add_f32_e32 v68, v70, v67
	v_sub_f32_e32 v69, v68, v70
	v_ldexp_f32 v64, v64, 1
	v_sub_f32_e32 v67, v67, v69
	v_add_f32_e32 v64, v64, v67
	v_add_f32_e32 v67, v68, v64
	v_sub_f32_e32 v68, v67, v68
	v_sub_f32_e32 v64, v64, v68
	v_add_f32_e32 v68, v65, v67
	v_sub_f32_e32 v69, v68, v65
	v_sub_f32_e32 v70, v68, v69
	v_sub_f32_e32 v66, v71, v66
	v_sub_f32_e32 v65, v65, v70
	v_sub_f32_e32 v67, v67, v69
	v_add_f32_e32 v65, v67, v65
	v_add_f32_e32 v67, v66, v64
	v_sub_f32_e32 v69, v67, v66
	v_sub_f32_e32 v70, v67, v69
	v_sub_f32_e32 v66, v66, v70
	v_sub_f32_e32 v64, v64, v69
	v_add_f32_e32 v65, v67, v65
	v_add_f32_e32 v64, v64, v66
	v_add_f32_e32 v66, v68, v65
	v_sub_f32_e32 v67, v66, v68
	v_sub_f32_e32 v65, v65, v67
	v_add_f32_e32 v64, v64, v65
	v_add_f32_e32 v64, v66, v64
	v_cndmask_b32_e32 v64, v179, v64, vcc
	v_cmp_lt_f32_e64 vcc, |v58|, s9
	s_nop 1
	v_cndmask_b32_e32 v58, v64, v58, vcc
	v_add_f32_e32 v29, v29, v58
	v_mul_f32_e64 v27, v29, -v27
	v_mul_f32_e32 v29, 0x3fb8aa3b, v27
	v_fma_f32 v58, v27, s38, -v29
	v_rndne_f32_e32 v64, v29
	v_fmac_f32_e32 v58, 0x32a5705f, v27
	v_sub_f32_e32 v29, v29, v64
	v_add_f32_e32 v29, v29, v58
	v_exp_f32_e32 v29, v29
	v_cvt_i32_f32_e32 v58, v64
	v_cmp_ngt_f32_e32 vcc, s39, v27
	v_ldexp_f32 v29, v29, v58
	s_nop 0
	v_cndmask_b32_e32 v29, 0, v29, vcc
	v_cmp_nlt_f32_e32 vcc, s78, v27
	s_nop 1
	v_cndmask_b32_e32 v27, v179, v29, vcc
	v_lshrrev_b32_e32 v29, 3, v230
	v_add_u32_e32 v29, s44, v29
	ds_write_b64 v29, v[26:27] offset:10240
.LBB0_1180:
	s_or_b64 exec, exec, s[0:1]
	v_lshlrev_b32_e32 v27, 16, v62
	v_and_b32_e32 v26, 0xffff0000, v62
	v_mul_f32_e32 v62, v20, v8
	v_fmac_f32_e32 v62, v24, v4
	v_lshlrev_b32_e32 v58, 16, v63
	v_fmac_f32_e32 v62, v12, v51
	v_fmac_f32_e32 v62, v14, v58
	v_mul_f32_e32 v24, 0xbfb8aa3b, v62
	v_and_b32_e32 v29, 0xffff0000, v63
	v_exp_f32_e32 v63, v24
	v_lshlrev_b32_e32 v24, 16, v59
	v_mul_f32_e32 v64, v18, v6
	v_fmac_f32_e32 v64, v22, v2
	v_add_f32_e32 v59, 1.0, v63
	v_mul_f32_e32 v63, v21, v9
	v_fmac_f32_e32 v63, v25, v5
	v_fmac_f32_e32 v63, v13, v48
	v_fmac_f32_e32 v63, v15, v29
	v_mul_f32_e32 v25, 0xbfb8aa3b, v63
	v_exp_f32_e32 v25, v25
	v_fmac_f32_e32 v64, v10, v50
	v_fmac_f32_e32 v64, v16, v27
	v_mul_f32_e32 v65, v19, v7
	v_add_f32_e32 v25, 1.0, v25
	v_mul_f32_e32 v22, 0xbfb8aa3b, v64
	v_fmac_f32_e32 v65, v23, v3
	v_rcp_f32_e32 v25, v25
	v_exp_f32_e32 v22, v22
	v_rcp_f32_e32 v59, v59
	v_fmac_f32_e32 v65, v11, v47
	v_fmac_f32_e32 v65, v17, v26
	v_mul_f32_e32 v23, 0xbfb8aa3b, v65
	v_exp_f32_e32 v23, v23
	v_mul_f32_e32 v25, v63, v25
	v_add_f32_e32 v22, 1.0, v22
	v_mul_f32_e32 v59, v62, v59
	v_mul_f32_e32 v63, v25, v25
	v_rcp_f32_e32 v22, v22
	v_fmac_f32_e32 v63, v59, v59
	v_add_f32_e32 v23, 1.0, v23
	v_rcp_f32_e32 v23, v23
	v_add_f32_dpp v63, v63, v63 row_ror:8 row_mask:0xf bank_mask:0xf bound_ctrl:1
	v_mul_f32_e32 v22, v64, v22
	v_mov_b32_e32 v64, v163
	v_add_f32_dpp v63, v63, v63 row_ror:4 row_mask:0xf bank_mask:0xf bound_ctrl:1
	v_mul_f32_e32 v23, v65, v23
	v_mul_f32_e32 v62, v57, v34
	v_add_f32_dpp v63, v63, v63 quad_perm:[2,3,0,1] row_mask:0xf bank_mask:0xf bound_ctrl:1
	v_fmac_f32_e32 v62, v56, v33
	v_mov_b32_e32 v65, v163
	v_add_f32_dpp v63, v63, v63 quad_perm:[1,0,3,2] row_mask:0xf bank_mask:0xf bound_ctrl:1
	v_fmac_f32_e32 v62, v35, v49
	v_fmac_f32_e32 v62, v36, v24
	v_mov_b32_dpp v64, v63 row_bcast:15 row_mask:0xa bank_mask:0xf
	v_add_f32_e32 v63, v63, v64
	v_mov_b32_e32 v64, v163
	v_mul_f32_e32 v56, 0xbfb8aa3b, v62
	v_exp_f32_e32 v56, v56
	v_mov_b32_dpp v64, v63 row_bcast:31 row_mask:0xc bank_mask:0xf
	v_add_f32_e32 v63, v63, v64
	v_mul_f32_e32 v64, v23, v23
	v_fmac_f32_e32 v64, v22, v22
	v_readlane_b32 s0, v63, 63
	v_add_f32_e32 v56, 1.0, v56
	v_add_f32_dpp v64, v64, v64 row_ror:8 row_mask:0xf bank_mask:0xf bound_ctrl:1
	v_add_f32_e32 v63, s0, v171
	v_rsq_f32_e32 v63, v63
	v_add_f32_dpp v64, v64, v64 row_ror:4 row_mask:0xf bank_mask:0xf bound_ctrl:1
	v_rcp_f32_e32 v56, v56
	s_ashr_i32 s25, s24, 31
	v_add_f32_dpp v64, v64, v64 quad_perm:[2,3,0,1] row_mask:0xf bank_mask:0xf bound_ctrl:1
	v_mul_f32_e32 v63, 0x3db504f3, v63
	v_mul_f32_e32 v59, v59, v63
	v_add_f32_dpp v64, v64, v64 quad_perm:[1,0,3,2] row_mask:0xf bank_mask:0xf bound_ctrl:1
	s_nop 1
	v_mov_b32_dpp v65, v64 row_bcast:15 row_mask:0xa bank_mask:0xf
	v_add_f32_e32 v64, v64, v65
	v_mov_b32_e32 v65, v163
	s_nop 1
	v_mov_b32_dpp v65, v64 row_bcast:31 row_mask:0xc bank_mask:0xf
	v_add_f32_e32 v64, v64, v65
	s_nop 0
	v_readlane_b32 s0, v64, 63
	s_nop 1
	v_add_f32_e32 v64, s0, v171
	v_rsq_f32_e32 v64, v64
	s_nop 0
	v_mul_f32_e32 v22, v22, v64
	v_mul_f32_e32 v23, v23, v64
	v_add_u32_e32 v64, 0x400, v28
	ds_write2_b32 v64, v22, v23 offset1:32
	v_mul_f32_e32 v22, v25, v63
	ds_write2_b32 v64, v59, v22 offset0:128 offset1:160
	v_mul_f32_e32 v22, v62, v56
	ds_write_b32 v37, v22 offset:8448
	s_and_saveexec_b64 s[0:1], s[4:5]
	s_cbranch_execz .LBB0_1182
.LBB0_1182:
	s_or_b64 exec, exec, s[0:1]
	v_lshlrev_b32_e32 v23, 16, v60
	v_mul_f32_e32 v60, v9, v48
	v_mul_f32_e32 v25, v8, v51
	v_fmac_f32_e32 v60, v21, v5
	v_lshlrev_b32_e32 v59, 16, v55
	v_and_b32_e32 v55, 0xffff0000, v55
	v_fmac_f32_e32 v25, v20, v4
	v_fmac_f32_e32 v60, v13, v29
	v_fmac_f32_e32 v25, v12, v58
	v_fmac_f32_e32 v60, v15, v55
	v_fmac_f32_e32 v25, v14, v59
	v_mul_f32_e32 v21, 0xbfb8aa3b, v60
	v_mul_f32_e32 v20, 0xbfb8aa3b, v25
	v_exp_f32_e32 v21, v21
	v_lshlrev_b32_e32 v56, 16, v61
	v_and_b32_e32 v22, 0xffff0000, v61
	v_exp_f32_e32 v20, v20
	v_mul_f32_e32 v61, v6, v50
	v_fmac_f32_e32 v61, v18, v2
	v_fmac_f32_e32 v61, v10, v27
	v_fmac_f32_e32 v61, v16, v56
	v_mul_f32_e32 v62, v7, v47
	v_add_f32_e32 v21, 1.0, v21
	v_mul_f32_e32 v18, 0xbfb8aa3b, v61
	v_add_f32_e32 v20, 1.0, v20
	v_fmac_f32_e32 v62, v19, v3
	v_rcp_f32_e32 v21, v21
	v_exp_f32_e32 v18, v18
	v_rcp_f32_e32 v20, v20
	v_fmac_f32_e32 v62, v11, v26
	v_fmac_f32_e32 v62, v17, v22
	v_mul_f32_e32 v19, 0xbfb8aa3b, v62
	v_exp_f32_e32 v19, v19
	v_mul_f32_e32 v21, v60, v21
	v_add_f32_e32 v18, 1.0, v18
	v_mul_f32_e32 v20, v25, v20
	v_mul_f32_e32 v60, v21, v21
	v_rcp_f32_e32 v18, v18
	v_fmac_f32_e32 v60, v20, v20
	v_add_f32_e32 v19, 1.0, v19
	v_rcp_f32_e32 v19, v19
	v_add_f32_dpp v60, v60, v60 row_ror:8 row_mask:0xf bank_mask:0xf bound_ctrl:1
	v_mul_f32_e32 v18, v61, v18
	v_mov_b32_e32 v61, v163
	v_add_f32_dpp v60, v60, v60 row_ror:4 row_mask:0xf bank_mask:0xf bound_ctrl:1
	v_mul_f32_e32 v19, v62, v19
	v_mul_f32_e32 v25, v34, v49
	v_add_f32_dpp v60, v60, v60 quad_perm:[2,3,0,1] row_mask:0xf bank_mask:0xf bound_ctrl:1
	v_fmac_f32_e32 v25, v57, v33
	v_mov_b32_e32 v62, v163
	v_add_f32_dpp v60, v60, v60 quad_perm:[1,0,3,2] row_mask:0xf bank_mask:0xf bound_ctrl:1
	v_fmac_f32_e32 v25, v35, v24
	v_fmac_f32_e32 v25, v36, v23
	v_mov_b32_dpp v61, v60 row_bcast:15 row_mask:0xa bank_mask:0xf
	v_add_f32_e32 v60, v60, v61
	v_mov_b32_e32 v61, v163
	v_mul_f32_e32 v57, 0xbfb8aa3b, v25
	v_exp_f32_e32 v57, v57
	v_mov_b32_dpp v61, v60 row_bcast:31 row_mask:0xc bank_mask:0xf
	v_add_f32_e32 v60, v60, v61
	v_mul_f32_e32 v61, v19, v19
	v_fmac_f32_e32 v61, v18, v18
	v_readlane_b32 s0, v60, 63
	v_add_f32_e32 v57, 1.0, v57
	v_add_f32_dpp v61, v61, v61 row_ror:8 row_mask:0xf bank_mask:0xf bound_ctrl:1
	v_add_f32_e32 v60, s0, v171
	v_rsq_f32_e32 v60, v60
	v_add_f32_dpp v61, v61, v61 row_ror:4 row_mask:0xf bank_mask:0xf bound_ctrl:1
	v_rcp_f32_e32 v57, v57
	s_ashr_i32 s23, s22, 31
	v_add_f32_dpp v61, v61, v61 quad_perm:[2,3,0,1] row_mask:0xf bank_mask:0xf bound_ctrl:1
	v_mul_f32_e32 v60, 0x3db504f3, v60
	v_mul_f32_e32 v20, v20, v60
	v_add_f32_dpp v61, v61, v61 quad_perm:[1,0,3,2] row_mask:0xf bank_mask:0xf bound_ctrl:1
	s_nop 1
	v_mov_b32_dpp v62, v61 row_bcast:15 row_mask:0xa bank_mask:0xf
	v_add_f32_e32 v61, v61, v62
	v_mov_b32_e32 v62, v163
	s_nop 1
	v_mov_b32_dpp v62, v61 row_bcast:31 row_mask:0xc bank_mask:0xf
	v_add_f32_e32 v61, v61, v62
	s_nop 0
	v_readlane_b32 s0, v61, 63
	s_nop 1
	v_add_f32_e32 v61, s0, v171
	v_rsq_f32_e32 v61, v61
	s_nop 0
	v_mul_f32_e32 v18, v18, v61
	v_mul_f32_e32 v19, v19, v61
	v_add_u32_e32 v61, 0x800, v28
	ds_write2_b32 v61, v18, v19 offset1:32
	v_mul_f32_e32 v18, v21, v60
	ds_write2_b32 v61, v20, v18 offset0:128 offset1:160
	v_mul_f32_e32 v18, v25, v57
	ds_write_b32 v37, v18 offset:8704
	s_and_saveexec_b64 s[0:1], s[4:5]
	s_cbranch_execz .LBB0_1184
.LBB0_1184:
	s_or_b64 exec, exec, s[0:1]
	v_mul_f32_e32 v18, v8, v58
	v_fmac_f32_e32 v18, v4, v51
	v_mul_f32_e32 v21, v6, v27
	v_mul_f32_e32 v51, v9, v29
	v_fmac_f32_e32 v21, v2, v50
	v_fmac_f32_e32 v51, v5, v48
	v_lshlrev_b32_e32 v60, 16, v54
	v_and_b32_e32 v54, 0xffff0000, v54
	v_lshlrev_b32_e32 v57, 16, v53
	v_fmac_f32_e32 v18, v12, v59
	v_fmac_f32_e32 v21, v10, v56
	v_fmac_f32_e32 v51, v13, v55
	v_fmac_f32_e32 v18, v14, v60
	v_fmac_f32_e32 v21, v16, v57
	v_fmac_f32_e32 v51, v15, v54
	v_mul_f32_e32 v19, 0xbfb8aa3b, v18
	v_mul_f32_e32 v25, 0xbfb8aa3b, v21
	v_mul_f32_e32 v48, 0xbfb8aa3b, v51
	v_exp_f32_e32 v19, v19
	v_exp_f32_e32 v50, v25
	v_exp_f32_e32 v48, v48
	v_lshlrev_b32_e32 v25, 16, v52
	v_add_f32_e32 v19, 1.0, v19
	v_add_f32_e32 v50, 1.0, v50
	v_mul_f32_e32 v52, v7, v26
	v_add_f32_e32 v48, 1.0, v48
	v_rcp_f32_e32 v19, v19
	v_fmac_f32_e32 v52, v3, v47
	v_rcp_f32_e32 v50, v50
	v_rcp_f32_e32 v48, v48
	v_and_b32_e32 v20, 0xffff0000, v53
	v_fmac_f32_e32 v52, v11, v22
	v_fmac_f32_e32 v52, v17, v20
	v_mul_f32_e32 v47, 0xbfb8aa3b, v52
	v_exp_f32_e32 v47, v47
	v_mul_f32_e32 v18, v18, v19
	v_mul_f32_e32 v19, v21, v50
	v_mul_f32_e32 v21, v51, v48
	v_mul_f32_e32 v50, v21, v21
	v_fmac_f32_e32 v50, v18, v18
	v_add_f32_e32 v47, 1.0, v47
	v_rcp_f32_e32 v47, v47
	v_add_f32_dpp v50, v50, v50 row_ror:8 row_mask:0xf bank_mask:0xf bound_ctrl:1
	v_mov_b32_e32 v51, v163
	v_mul_f32_e32 v48, v34, v24
	v_add_f32_dpp v50, v50, v50 row_ror:4 row_mask:0xf bank_mask:0xf bound_ctrl:1
	v_mul_f32_e32 v47, v52, v47
	v_fmac_f32_e32 v48, v33, v49
	v_add_f32_dpp v50, v50, v50 quad_perm:[2,3,0,1] row_mask:0xf bank_mask:0xf bound_ctrl:1
	v_mov_b32_e32 v52, v163
	v_fmac_f32_e32 v48, v35, v23
	v_add_f32_dpp v50, v50, v50 quad_perm:[1,0,3,2] row_mask:0xf bank_mask:0xf bound_ctrl:1
	v_fmac_f32_e32 v48, v36, v25
	v_mul_f32_e32 v49, 0xbfb8aa3b, v48
	v_mov_b32_dpp v51, v50 row_bcast:15 row_mask:0xa bank_mask:0xf
	v_add_f32_e32 v50, v50, v51
	v_mov_b32_e32 v51, v163
	v_exp_f32_e32 v49, v49
	s_ashr_i32 s21, s20, 31
	v_mov_b32_dpp v51, v50 row_bcast:31 row_mask:0xc bank_mask:0xf
	v_add_f32_e32 v50, v50, v51
	v_mul_f32_e32 v51, v47, v47
	v_fmac_f32_e32 v51, v19, v19
	v_readlane_b32 s0, v50, 63
	v_add_f32_e32 v49, 1.0, v49
	v_add_f32_dpp v51, v51, v51 row_ror:8 row_mask:0xf bank_mask:0xf bound_ctrl:1
	v_add_f32_e32 v50, s0, v171
	v_rsq_f32_e32 v50, v50
	v_add_f32_dpp v51, v51, v51 row_ror:4 row_mask:0xf bank_mask:0xf bound_ctrl:1
	v_rcp_f32_e32 v49, v49
	v_mul_f32_e32 v50, 0x3db504f3, v50
	v_add_f32_dpp v51, v51, v51 quad_perm:[2,3,0,1] row_mask:0xf bank_mask:0xf bound_ctrl:1
	v_mul_f32_e32 v18, v18, v50
	s_nop 0
	v_add_f32_dpp v51, v51, v51 quad_perm:[1,0,3,2] row_mask:0xf bank_mask:0xf bound_ctrl:1
	s_nop 1
	v_mov_b32_dpp v52, v51 row_bcast:15 row_mask:0xa bank_mask:0xf
	v_add_f32_e32 v51, v51, v52
	v_mov_b32_e32 v52, v163
	s_nop 1
	v_mov_b32_dpp v52, v51 row_bcast:31 row_mask:0xc bank_mask:0xf
	v_add_f32_e32 v51, v51, v52
	s_nop 0
	v_readlane_b32 s0, v51, 63
	s_nop 1
	v_add_f32_e32 v51, s0, v171
	v_rsq_f32_e32 v51, v51
	s_nop 0
	v_mul_f32_e32 v19, v19, v51
	v_mul_f32_e32 v47, v47, v51
	v_add_u32_e32 v51, 0xc00, v28
	ds_write2_b32 v51, v19, v47 offset1:32
	v_mul_f32_e32 v19, v21, v50
	ds_write2_b32 v51, v18, v19 offset0:128 offset1:160
	v_mul_f32_e32 v18, v48, v49
	ds_write_b32 v37, v18 offset:8960
	s_and_saveexec_b64 s[0:1], s[4:5]
	s_cbranch_execz .LBB0_1186
.LBB0_1186:
	s_or_b64 exec, exec, s[0:1]
	v_lshlrev_b32_e32 v47, 16, v45
	v_and_b32_e32 v21, 0xffff0000, v45
	v_mul_f32_e32 v45, v6, v56
	v_fmac_f32_e32 v45, v2, v27
	v_fmac_f32_e32 v45, v10, v57
	v_fmac_f32_e32 v45, v16, v47
	v_mul_f32_e32 v27, 0xbfb8aa3b, v45
	v_exp_f32_e32 v49, v27
	v_lshlrev_b32_e32 v27, 16, v44
	v_mul_f32_e32 v18, v8, v59
	v_lshlrev_b32_e32 v48, 16, v46
	v_add_f32_e32 v44, 1.0, v49
	v_mul_f32_e32 v49, v9, v55
	v_fmac_f32_e32 v49, v5, v29
	v_and_b32_e32 v46, 0xffff0000, v46
	v_fmac_f32_e32 v18, v4, v58
	v_fmac_f32_e32 v49, v13, v54
	v_fmac_f32_e32 v18, v12, v60
	v_fmac_f32_e32 v49, v15, v46
	v_fmac_f32_e32 v18, v14, v48
	v_mul_f32_e32 v29, 0xbfb8aa3b, v49
	v_mul_f32_e32 v19, 0xbfb8aa3b, v18
	v_exp_f32_e32 v29, v29
	v_exp_f32_e32 v19, v19
	v_mul_f32_e32 v50, v7, v22
	v_fmac_f32_e32 v50, v3, v26
	v_add_f32_e32 v29, 1.0, v29
	v_add_f32_e32 v19, 1.0, v19
	v_rcp_f32_e32 v29, v29
	v_rcp_f32_e32 v19, v19
	v_fmac_f32_e32 v50, v11, v20
	v_rcp_f32_e32 v44, v44
	v_fmac_f32_e32 v50, v17, v21
	v_mul_f32_e32 v26, 0xbfb8aa3b, v50
	v_exp_f32_e32 v26, v26
	v_mul_f32_e32 v29, v49, v29
	v_mul_f32_e32 v18, v18, v19
	v_mul_f32_e32 v19, v45, v44
	v_mul_f32_e32 v45, v29, v29
	v_fmac_f32_e32 v45, v18, v18
	v_add_f32_e32 v26, 1.0, v26
	v_rcp_f32_e32 v26, v26
	v_add_f32_dpp v45, v45, v45 row_ror:8 row_mask:0xf bank_mask:0xf bound_ctrl:1
	v_mov_b32_e32 v49, v163
	v_mul_f32_e32 v44, v34, v23
	v_add_f32_dpp v45, v45, v45 row_ror:4 row_mask:0xf bank_mask:0xf bound_ctrl:1
	v_mul_f32_e32 v26, v50, v26
	v_fmac_f32_e32 v44, v33, v24
	v_add_f32_dpp v45, v45, v45 quad_perm:[2,3,0,1] row_mask:0xf bank_mask:0xf bound_ctrl:1
	v_mov_b32_e32 v50, v163
	v_fmac_f32_e32 v44, v35, v25
	v_add_f32_dpp v45, v45, v45 quad_perm:[1,0,3,2] row_mask:0xf bank_mask:0xf bound_ctrl:1
	v_fmac_f32_e32 v44, v36, v27
	v_mul_f32_e32 v24, 0xbfb8aa3b, v44
	v_mov_b32_dpp v49, v45 row_bcast:15 row_mask:0xa bank_mask:0xf
	v_add_f32_e32 v45, v45, v49
	v_mov_b32_e32 v49, v163
	v_exp_f32_e32 v24, v24
	s_ashr_i32 s19, s18, 31
	v_mov_b32_dpp v49, v45 row_bcast:31 row_mask:0xc bank_mask:0xf
	v_add_f32_e32 v45, v45, v49
	v_mul_f32_e32 v49, v26, v26
	v_fmac_f32_e32 v49, v19, v19
	v_readlane_b32 s0, v45, 63
	v_add_f32_e32 v24, 1.0, v24
	v_add_f32_dpp v49, v49, v49 row_ror:8 row_mask:0xf bank_mask:0xf bound_ctrl:1
	v_add_f32_e32 v45, s0, v171
	v_rsq_f32_e32 v45, v45
	v_add_f32_dpp v49, v49, v49 row_ror:4 row_mask:0xf bank_mask:0xf bound_ctrl:1
	v_rcp_f32_e32 v24, v24
	v_mul_f32_e32 v45, 0x3db504f3, v45
	v_add_f32_dpp v49, v49, v49 quad_perm:[2,3,0,1] row_mask:0xf bank_mask:0xf bound_ctrl:1
	v_mul_f32_e32 v18, v18, v45
	s_nop 0
	v_add_f32_dpp v49, v49, v49 quad_perm:[1,0,3,2] row_mask:0xf bank_mask:0xf bound_ctrl:1
	s_nop 1
	v_mov_b32_dpp v50, v49 row_bcast:15 row_mask:0xa bank_mask:0xf
	v_add_f32_e32 v49, v49, v50
	v_mov_b32_e32 v50, v163
	s_nop 1
	v_mov_b32_dpp v50, v49 row_bcast:31 row_mask:0xc bank_mask:0xf
	v_add_f32_e32 v49, v49, v50
	s_nop 0
	v_readlane_b32 s0, v49, 63
	s_nop 1
	v_add_f32_e32 v49, s0, v171
	v_rsq_f32_e32 v49, v49
	s_nop 0
	v_mul_f32_e32 v19, v19, v49
	v_mul_f32_e32 v26, v26, v49
	v_add_u32_e32 v49, 0x1000, v28
	ds_write2_b32 v49, v19, v26 offset1:32
	v_mul_f32_e32 v19, v29, v45
	ds_write2_b32 v49, v18, v19 offset0:128 offset1:160
	v_mul_f32_e32 v18, v44, v24
	ds_write_b32 v37, v18 offset:9216
	s_and_saveexec_b64 s[0:1], s[4:5]
	s_cbranch_execz .LBB0_1188
.LBB0_1188:
	s_or_b64 exec, exec, s[0:1]
	v_lshlrev_b32_e32 v44, 16, v43
	v_and_b32_e32 v29, 0xffff0000, v43
	v_lshlrev_b32_e32 v43, 16, v42
	v_and_b32_e32 v24, 0xffff0000, v42
	v_mul_f32_e32 v42, v6, v57
	v_fmac_f32_e32 v42, v2, v56
	v_fmac_f32_e32 v42, v10, v47
	v_fmac_f32_e32 v42, v16, v43
	v_mul_f32_e32 v26, 0xbfb8aa3b, v42
	v_exp_f32_e32 v45, v26
	v_mul_f32_e32 v18, v8, v60
	v_lshlrev_b32_e32 v26, 16, v41
	v_fmac_f32_e32 v18, v4, v59
	v_add_f32_e32 v41, 1.0, v45
	v_mul_f32_e32 v45, v9, v54
	v_fmac_f32_e32 v45, v5, v55
	v_fmac_f32_e32 v18, v12, v48
	v_fmac_f32_e32 v45, v13, v46
	v_fmac_f32_e32 v18, v14, v44
	v_fmac_f32_e32 v45, v15, v29
	v_mul_f32_e32 v19, 0xbfb8aa3b, v18
	v_mul_f32_e32 v49, 0xbfb8aa3b, v45
	v_exp_f32_e32 v19, v19
	v_exp_f32_e32 v49, v49
	v_mul_f32_e32 v50, v7, v20
	v_fmac_f32_e32 v50, v3, v22
	v_add_f32_e32 v19, 1.0, v19
	v_add_f32_e32 v49, 1.0, v49
	v_rcp_f32_e32 v19, v19
	v_rcp_f32_e32 v41, v41
	v_rcp_f32_e32 v49, v49
	v_fmac_f32_e32 v50, v11, v21
	v_fmac_f32_e32 v50, v17, v24
	v_mul_f32_e32 v22, 0xbfb8aa3b, v50
	v_exp_f32_e32 v22, v22
	v_mul_f32_e32 v18, v18, v19
	v_mul_f32_e32 v19, v42, v41
	v_mul_f32_e32 v41, v45, v49
	v_mul_f32_e32 v45, v41, v41
	v_fmac_f32_e32 v45, v18, v18
	v_add_f32_e32 v22, 1.0, v22
	v_rcp_f32_e32 v22, v22
	v_add_f32_dpp v45, v45, v45 row_ror:8 row_mask:0xf bank_mask:0xf bound_ctrl:1
	v_mov_b32_e32 v49, v163
	v_mul_f32_e32 v42, v34, v25
	v_add_f32_dpp v45, v45, v45 row_ror:4 row_mask:0xf bank_mask:0xf bound_ctrl:1
	v_mul_f32_e32 v22, v50, v22
	v_fmac_f32_e32 v42, v33, v23
	v_add_f32_dpp v45, v45, v45 quad_perm:[2,3,0,1] row_mask:0xf bank_mask:0xf bound_ctrl:1
	v_mov_b32_e32 v50, v163
	v_fmac_f32_e32 v42, v35, v27
	v_add_f32_dpp v45, v45, v45 quad_perm:[1,0,3,2] row_mask:0xf bank_mask:0xf bound_ctrl:1
	v_fmac_f32_e32 v42, v36, v26
	v_mul_f32_e32 v23, 0xbfb8aa3b, v42
	v_mov_b32_dpp v49, v45 row_bcast:15 row_mask:0xa bank_mask:0xf
	v_add_f32_e32 v45, v45, v49
	v_mov_b32_e32 v49, v163
	v_exp_f32_e32 v23, v23
	s_ashr_i32 s17, s16, 31
	v_mov_b32_dpp v49, v45 row_bcast:31 row_mask:0xc bank_mask:0xf
	v_add_f32_e32 v45, v45, v49
	v_mul_f32_e32 v49, v22, v22
	v_fmac_f32_e32 v49, v19, v19
	v_readlane_b32 s0, v45, 63
	v_add_f32_e32 v23, 1.0, v23
	v_add_f32_dpp v49, v49, v49 row_ror:8 row_mask:0xf bank_mask:0xf bound_ctrl:1
	v_add_f32_e32 v45, s0, v171
	v_rsq_f32_e32 v45, v45
	v_add_f32_dpp v49, v49, v49 row_ror:4 row_mask:0xf bank_mask:0xf bound_ctrl:1
	v_rcp_f32_e32 v23, v23
	v_mul_f32_e32 v45, 0x3db504f3, v45
	v_add_f32_dpp v49, v49, v49 quad_perm:[2,3,0,1] row_mask:0xf bank_mask:0xf bound_ctrl:1
	v_mul_f32_e32 v18, v18, v45
	s_nop 0
	v_add_f32_dpp v49, v49, v49 quad_perm:[1,0,3,2] row_mask:0xf bank_mask:0xf bound_ctrl:1
	s_nop 1
	v_mov_b32_dpp v50, v49 row_bcast:15 row_mask:0xa bank_mask:0xf
	v_add_f32_e32 v49, v49, v50
	v_mov_b32_e32 v50, v163
	s_nop 1
	v_mov_b32_dpp v50, v49 row_bcast:31 row_mask:0xc bank_mask:0xf
	v_add_f32_e32 v49, v49, v50
	s_nop 0
	v_readlane_b32 s0, v49, 63
	s_nop 1
	v_add_f32_e32 v49, s0, v171
	v_rsq_f32_e32 v49, v49
	s_nop 0
	v_mul_f32_e32 v19, v19, v49
	v_mul_f32_e32 v22, v22, v49
	v_add_u32_e32 v49, 0x1400, v28
	ds_write2_b32 v49, v19, v22 offset1:32
	v_mul_f32_e32 v19, v41, v45
	ds_write2_b32 v49, v18, v19 offset0:128 offset1:160
	v_mul_f32_e32 v18, v42, v23
	ds_write_b32 v37, v18 offset:9472
	s_and_saveexec_b64 s[0:1], s[4:5]
	s_cbranch_execz .LBB0_1190
.LBB0_1190:
	s_or_b64 exec, exec, s[0:1]
	v_lshlrev_b32_e32 v41, 16, v39
	v_and_b32_e32 v22, 0xffff0000, v39
	v_mul_f32_e32 v39, v6, v47
	v_fmac_f32_e32 v39, v2, v57
	v_fmac_f32_e32 v39, v10, v43
	v_fmac_f32_e32 v39, v16, v41
	v_mul_f32_e32 v23, 0xbfb8aa3b, v39
	v_exp_f32_e32 v45, v23
	v_mul_f32_e32 v18, v8, v48
	v_lshlrev_b32_e32 v23, 16, v38
	v_fmac_f32_e32 v18, v4, v60
	v_add_f32_e32 v38, 1.0, v45
	v_mul_f32_e32 v45, v9, v46
	v_fmac_f32_e32 v45, v5, v54
	v_lshlrev_b32_e32 v42, 16, v40
	v_and_b32_e32 v40, 0xffff0000, v40
	v_fmac_f32_e32 v18, v12, v44
	v_fmac_f32_e32 v45, v13, v29
	v_fmac_f32_e32 v18, v14, v42
	v_fmac_f32_e32 v45, v15, v40
	v_mul_f32_e32 v19, 0xbfb8aa3b, v18
	v_mul_f32_e32 v49, 0xbfb8aa3b, v45
	v_exp_f32_e32 v19, v19
	v_exp_f32_e32 v49, v49
	v_mul_f32_e32 v50, v7, v21
	v_fmac_f32_e32 v50, v3, v20
	v_add_f32_e32 v19, 1.0, v19
	v_add_f32_e32 v49, 1.0, v49
	v_rcp_f32_e32 v19, v19
	v_rcp_f32_e32 v38, v38
	v_rcp_f32_e32 v49, v49
	v_fmac_f32_e32 v50, v11, v24
	v_fmac_f32_e32 v50, v17, v22
	v_mul_f32_e32 v20, 0xbfb8aa3b, v50
	v_exp_f32_e32 v20, v20
	v_mul_f32_e32 v18, v18, v19
	v_mul_f32_e32 v19, v39, v38
	v_mul_f32_e32 v38, v45, v49
	v_mul_f32_e32 v45, v38, v38
	v_fmac_f32_e32 v45, v18, v18
	v_add_f32_e32 v20, 1.0, v20
	v_rcp_f32_e32 v20, v20
	v_add_f32_dpp v45, v45, v45 row_ror:8 row_mask:0xf bank_mask:0xf bound_ctrl:1
	v_mov_b32_e32 v49, v163
	v_mul_f32_e32 v39, v34, v27
	v_add_f32_dpp v45, v45, v45 row_ror:4 row_mask:0xf bank_mask:0xf bound_ctrl:1
	v_mul_f32_e32 v20, v50, v20
	v_fmac_f32_e32 v39, v33, v25
	v_add_f32_dpp v45, v45, v45 quad_perm:[2,3,0,1] row_mask:0xf bank_mask:0xf bound_ctrl:1
	v_mov_b32_e32 v50, v163
	v_fmac_f32_e32 v39, v35, v26
	v_add_f32_dpp v45, v45, v45 quad_perm:[1,0,3,2] row_mask:0xf bank_mask:0xf bound_ctrl:1
	v_fmac_f32_e32 v39, v36, v23
	v_mul_f32_e32 v25, 0xbfb8aa3b, v39
	v_mov_b32_dpp v49, v45 row_bcast:15 row_mask:0xa bank_mask:0xf
	v_add_f32_e32 v45, v45, v49
	v_mov_b32_e32 v49, v163
	v_exp_f32_e32 v25, v25
	s_ashr_i32 s15, s14, 31
	v_mov_b32_dpp v49, v45 row_bcast:31 row_mask:0xc bank_mask:0xf
	v_add_f32_e32 v45, v45, v49
	v_mul_f32_e32 v49, v20, v20
	v_fmac_f32_e32 v49, v19, v19
	v_readlane_b32 s0, v45, 63
	v_add_f32_e32 v25, 1.0, v25
	v_add_f32_dpp v49, v49, v49 row_ror:8 row_mask:0xf bank_mask:0xf bound_ctrl:1
	v_add_f32_e32 v45, s0, v171
	v_rsq_f32_e32 v45, v45
	v_add_f32_dpp v49, v49, v49 row_ror:4 row_mask:0xf bank_mask:0xf bound_ctrl:1
	v_rcp_f32_e32 v25, v25
	v_mul_f32_e32 v45, 0x3db504f3, v45
	v_add_f32_dpp v49, v49, v49 quad_perm:[2,3,0,1] row_mask:0xf bank_mask:0xf bound_ctrl:1
	v_mul_f32_e32 v18, v18, v45
	s_nop 0
	v_add_f32_dpp v49, v49, v49 quad_perm:[1,0,3,2] row_mask:0xf bank_mask:0xf bound_ctrl:1
	s_nop 1
	v_mov_b32_dpp v50, v49 row_bcast:15 row_mask:0xa bank_mask:0xf
	v_add_f32_e32 v49, v49, v50
	v_mov_b32_e32 v50, v163
	s_nop 1
	v_mov_b32_dpp v50, v49 row_bcast:31 row_mask:0xc bank_mask:0xf
	v_add_f32_e32 v49, v49, v50
	s_nop 0
	v_readlane_b32 s0, v49, 63
	s_nop 1
	v_add_f32_e32 v49, s0, v171
	v_rsq_f32_e32 v49, v49
	s_nop 0
	v_mul_f32_e32 v19, v19, v49
	v_mul_f32_e32 v20, v20, v49
	v_add_u32_e32 v49, 0x1800, v28
	ds_write2_b32 v49, v19, v20 offset1:32
	v_mul_f32_e32 v19, v38, v45
	ds_write2_b32 v49, v18, v19 offset0:128 offset1:160
	v_mul_f32_e32 v18, v39, v25
	ds_write_b32 v37, v18 offset:9728
	s_and_saveexec_b64 s[0:1], s[4:5]
	s_cbranch_execz .LBB0_1192
.LBB0_1192:
	s_or_b64 exec, exec, s[0:1]
	v_mul_f32_e32 v9, v9, v29
	v_mul_f32_e32 v8, v8, v44
	v_fmac_f32_e32 v9, v5, v46
	v_and_b32_e32 v19, 0xffff0000, v32
	v_fmac_f32_e32 v8, v4, v48
	v_fmac_f32_e32 v9, v13, v40
	v_lshlrev_b32_e32 v18, 16, v32
	v_fmac_f32_e32 v8, v12, v42
	v_fmac_f32_e32 v9, v15, v19
	v_fmac_f32_e32 v8, v14, v18
	v_mul_f32_e32 v5, 0xbfb8aa3b, v9
	v_mul_f32_e32 v4, 0xbfb8aa3b, v8
	v_exp_f32_e32 v5, v5
	v_exp_f32_e32 v4, v4
	v_mul_f32_e32 v7, v7, v24
	v_mul_f32_e32 v6, v6, v43
	v_add_f32_e32 v5, 1.0, v5
	v_add_f32_e32 v4, 1.0, v4
	v_fmac_f32_e32 v7, v3, v21
	v_rcp_f32_e32 v5, v5
	v_and_b32_e32 v25, 0xffff0000, v31
	v_fmac_f32_e32 v6, v2, v47
	v_rcp_f32_e32 v4, v4
	v_fmac_f32_e32 v7, v11, v22
	v_lshlrev_b32_e32 v20, 16, v31
	v_fmac_f32_e32 v6, v10, v41
	v_fmac_f32_e32 v7, v17, v25
	v_fmac_f32_e32 v6, v16, v20
	v_mul_f32_e32 v3, 0xbfb8aa3b, v7
	v_mul_f32_e32 v2, 0xbfb8aa3b, v6
	v_exp_f32_e32 v3, v3
	v_mul_f32_e32 v5, v9, v5
	v_exp_f32_e32 v2, v2
	v_mul_f32_e32 v4, v8, v4
	v_mul_f32_e32 v8, v5, v5
	v_fmac_f32_e32 v8, v4, v4
	v_add_f32_e32 v3, 1.0, v3
	v_add_f32_e32 v2, 1.0, v2
	v_add_f32_dpp v8, v8, v8 row_ror:8 row_mask:0xf bank_mask:0xf bound_ctrl:1
	v_rcp_f32_e32 v3, v3
	v_rcp_f32_e32 v2, v2
	v_add_f32_dpp v8, v8, v8 row_ror:4 row_mask:0xf bank_mask:0xf bound_ctrl:1
	v_mov_b32_e32 v9, v163
	v_mul_f32_e32 v3, v7, v3
	v_add_f32_dpp v8, v8, v8 quad_perm:[2,3,0,1] row_mask:0xf bank_mask:0xf bound_ctrl:1
	v_mul_f32_e32 v2, v6, v2
	v_mul_f32_e32 v6, v34, v26
	v_add_f32_dpp v8, v8, v8 quad_perm:[1,0,3,2] row_mask:0xf bank_mask:0xf bound_ctrl:1
	v_fmac_f32_e32 v6, v33, v27
	v_lshlrev_b32_e32 v10, 16, v30
	v_mov_b32_dpp v9, v8 row_bcast:15 row_mask:0xa bank_mask:0xf
	v_add_f32_e32 v8, v8, v9
	v_mov_b32_e32 v9, v163
	v_fmac_f32_e32 v6, v35, v23
	v_fmac_f32_e32 v6, v36, v10
	v_mov_b32_dpp v9, v8 row_bcast:31 row_mask:0xc bank_mask:0xf
	v_add_f32_e32 v8, v8, v9
	v_mul_f32_e32 v9, v3, v3
	v_fmac_f32_e32 v9, v2, v2
	v_mov_b32_e32 v10, v163
	v_mul_f32_e32 v7, 0xbfb8aa3b, v6
	v_add_f32_dpp v9, v9, v9 row_ror:8 row_mask:0xf bank_mask:0xf bound_ctrl:1
	v_exp_f32_e32 v7, v7
	v_readlane_b32 s0, v8, 63
	v_add_f32_dpp v9, v9, v9 row_ror:4 row_mask:0xf bank_mask:0xf bound_ctrl:1
	s_ashr_i32 s13, s12, 31
	v_add_f32_e32 v8, s0, v171
	v_add_f32_dpp v9, v9, v9 quad_perm:[2,3,0,1] row_mask:0xf bank_mask:0xf bound_ctrl:1
	v_rsq_f32_e32 v8, v8
	v_add_f32_e32 v7, 1.0, v7
	v_add_f32_dpp v9, v9, v9 quad_perm:[1,0,3,2] row_mask:0xf bank_mask:0xf bound_ctrl:1
	v_rcp_f32_e32 v7, v7
	v_mul_f32_e32 v8, 0x3db504f3, v8
	v_mov_b32_dpp v10, v9 row_bcast:15 row_mask:0xa bank_mask:0xf
	v_add_f32_e32 v9, v9, v10
	v_mov_b32_e32 v10, v163
	v_mul_f32_e32 v4, v4, v8
	s_nop 0
	v_mov_b32_dpp v10, v9 row_bcast:31 row_mask:0xc bank_mask:0xf
	v_add_f32_e32 v9, v9, v10
	s_nop 0
	v_readlane_b32 s0, v9, 63
	s_nop 1
	v_add_f32_e32 v9, s0, v171
	v_rsq_f32_e32 v9, v9
	s_nop 0
	v_mul_f32_e32 v2, v2, v9
	v_mul_f32_e32 v3, v3, v9
	v_add_u32_e32 v9, 0x1c00, v28
	ds_write2_b32 v9, v2, v3 offset1:32
	v_mul_f32_e32 v2, v5, v8
	ds_write2_b32 v9, v4, v2 offset0:128 offset1:160
	v_mul_f32_e32 v2, v6, v7
	ds_write_b32 v37, v2 offset:9984
	s_and_saveexec_b64 s[0:1], s[4:5]
	s_cbranch_execz .LBB0_1194
.LBB0_1194:
	s_or_b64 exec, exec, s[0:1]
	s_add_i32 s0, s46, s47
	s_ashr_i32 s1, s0, 31
	v_lshlrev_b32_e32 v2, 3, v131
	v_and_b32_e32 v132, 0x180, v2
	v_lshlrev_b32_e32 v2, 2, v130
	s_lshl_b64 s[0:1], s[0:1], 14
	v_and_b32_e32 v162, 60, v2
	v_or_b32_e32 v2, s0, v132
	v_readlane_b32 s56, v245, 6
	v_or3_b32 v164, v2, s42, v162
	v_mov_b32_e32 v165, s1
	v_readlane_b32 s60, v245, 10
	v_readlane_b32 s61, v245, 11
	s_movk_i32 s0, 0x2000
	v_and_b32_e32 v134, 64, v1
	v_lshl_add_u64 v[2:3], v[164:165], 2, s[60:61]
	v_add_co_u32_e32 v4, vcc, s76, v2
	global_load_dwordx4 v[98:101], v[2:3], off nt
	global_load_dwordx4 v[94:97], v[2:3], off offset:2048 nt
	v_addc_co_u32_e32 v5, vcc, 0, v3, vcc
	v_add_co_u32_e32 v14, vcc, s0, v2
	s_movk_i32 s0, 0x5000
	s_nop 0
	v_addc_co_u32_e32 v15, vcc, 0, v3, vcc
	v_add_co_u32_e32 v6, vcc, s97, v2
	global_load_dwordx4 v[74:77], v[14:15], off nt
	global_load_dwordx4 v[70:73], v[14:15], off offset:2048 nt
	v_addc_co_u32_e32 v7, vcc, 0, v3, vcc
	v_add_co_u32_e32 v8, vcc, s96, v2
	v_xor_b32_e32 v133, 16, v1
	s_nop 0
	v_addc_co_u32_e32 v9, vcc, 0, v3, vcc
	global_load_dwordx4 v[122:125], v[4:5], off offset:2048 nt
	global_load_dwordx4 v[102:105], v[6:7], off offset:2048 nt
	global_load_dwordx4 v[106:109], v[8:9], off offset:-4096 nt
	global_load_dwordx4 v[58:61], v[8:9], off nt
	v_add_co_u32_e32 v4, vcc, s0, v2
	s_mov_b32 s0, 0x8000
	s_nop 0
	v_addc_co_u32_e32 v5, vcc, 0, v3, vcc
	v_add_co_u32_e32 v6, vcc, s84, v2
	v_add_u32_e32 v134, 64, v134
	s_nop 0
	v_addc_co_u32_e32 v7, vcc, 0, v3, vcc
	global_load_dwordx4 v[110:113], v[8:9], off offset:2048 nt
	global_load_dwordx4 v[90:93], v[6:7], off offset:-4096 nt
	global_load_dwordx4 v[46:49], v[6:7], off nt
	global_load_dwordx4 v[42:45], v[6:7], off offset:2048 nt
	v_add_co_u32_e32 v6, vcc, s85, v2
	s_lshl_b32 s28, s45, 5
	s_nop 0
	v_addc_co_u32_e32 v7, vcc, 0, v3, vcc
	v_add_co_u32_e32 v8, vcc, s0, v2
	s_mov_b32 s0, 0xb000
	s_nop 0
	v_addc_co_u32_e32 v9, vcc, 0, v3, vcc
	global_load_dwordx4 v[118:121], v[4:5], off offset:2048 nt
	global_load_dwordx4 v[66:69], v[6:7], off offset:2048 nt
	global_load_dwordx4 v[86:89], v[8:9], off offset:-4096 nt
	global_load_dwordx4 v[30:33], v[8:9], off nt
	v_add_co_u32_e32 v4, vcc, s75, v2
	s_add_i32 s30, s28, 0
	s_nop 0
	v_addc_co_u32_e32 v5, vcc, 0, v3, vcc
	v_add_co_u32_e32 v6, vcc, s80, v2
	v_and_b32_e32 v130, 15, v130
	s_nop 0
	v_addc_co_u32_e32 v7, vcc, 0, v3, vcc
	global_load_dwordx4 v[82:85], v[8:9], off offset:2048 nt
	global_load_dwordx4 v[54:57], v[6:7], off offset:-4096 nt
	global_load_dwordx4 v[26:29], v[6:7], off nt
	global_load_dwordx4 v[22:25], v[6:7], off offset:2048 nt
	v_add_co_u32_e32 v6, vcc, s0, v2
	s_mov_b32 s0, 0xd000
	s_nop 0
	v_addc_co_u32_e32 v7, vcc, 0, v3, vcc
	v_add_co_u32_e32 v8, vcc, s77, v2
	s_mov_b32 s29, 0
	s_nop 0
	v_addc_co_u32_e32 v9, vcc, 0, v3, vcc
	global_load_dwordx4 v[114:117], v[4:5], off offset:2048 nt
	global_load_dwordx4 v[38:41], v[6:7], off offset:2048 nt
	global_load_dwordx4 v[50:53], v[8:9], off offset:-4096 nt
	global_load_dwordx4 v[18:21], v[8:9], off nt
	v_add_co_u32_e32 v4, vcc, s0, v2
	s_mov_b32 s0, 0xe000
	s_nop 0
	v_addc_co_u32_e32 v5, vcc, 0, v3, vcc
	v_add_co_u32_e32 v6, vcc, s0, v2
	s_mov_b32 s0, 0xf000
	s_nop 0
	v_addc_co_u32_e32 v7, vcc, 0, v3, vcc
	v_add_co_u32_e32 v16, vcc, s0, v2
	global_load_dwordx4 v[62:65], v[8:9], off offset:2048 nt
	global_load_dwordx4 v[34:37], v[6:7], off offset:-4096 nt
	global_load_dwordx4 v[10:13], v[6:7], off nt
	s_nop 0
	global_load_dwordx4 v[6:9], v[6:7], off offset:2048 nt
	v_addc_co_u32_e32 v17, vcc, 0, v3, vcc
	global_load_dwordx4 v[78:81], v[4:5], off offset:2048 nt
	s_nop 0
	global_load_dwordx4 v[2:5], v[16:17], off nt
	global_load_dwordx4 v[126:129], v[14:15], off offset:-4096 nt
	s_nop 0
	global_load_dwordx4 v[14:17], v[16:17], off offset:2048 nt
	v_cmp_lt_i32_e32 vcc, v133, v134
	s_add_i32 s0, s44, 0x2000
	v_cmp_gt_u32_e64 s[6:7], 16, v131
	v_cndmask_b32_e32 v133, v1, v133, vcc
	v_lshlrev_b32_e32 v181, 2, v133
	v_xor_b32_e32 v133, 32, v1
	v_cmp_lt_i32_e32 vcc, v133, v134
	v_add_u32_e32 v185, s44, v132
	s_add_i32 s30, s30, 0x14200
	v_cndmask_b32_e32 v133, v1, v133, vcc
	v_lshlrev_b32_e32 v183, 2, v133
	v_lshl_add_u32 v187, v130, 4, s0
	s_add_i32 s31, s44, 0x2800
	v_readlane_b32 s57, v245, 7
	v_readlane_b32 s58, v245, 8
	v_readlane_b32 s59, v245, 9
	v_readlane_b32 s62, v245, 12
	v_readlane_b32 s63, v245, 13
	v_readlane_b32 s64, v245, 14
	v_readlane_b32 s65, v245, 15
	v_readlane_b32 s66, v245, 16
	v_readlane_b32 s67, v245, 17
	v_readlane_b32 s68, v245, 18
	v_readlane_b32 s69, v245, 19
	v_readlane_b32 s70, v245, 20
	v_readlane_b32 s71, v245, 21
	s_branch .LBB0_1196

	.amdhsa_kernel _Z7hyb_fwd4Args
		.amdhsa_group_segment_fixed_size 0
		.amdhsa_private_segment_fixed_size 0
		.amdhsa_kernarg_size 496
		.amdhsa_user_sgpr_count 2
		.amdhsa_user_sgpr_dispatch_ptr 0
		.amdhsa_user_sgpr_queue_ptr 0
		.amdhsa_user_sgpr_kernarg_segment_ptr 1
		.amdhsa_user_sgpr_dispatch_id 0
		.amdhsa_user_sgpr_kernarg_preload_length 0
		.amdhsa_user_sgpr_kernarg_preload_offset 0
		.amdhsa_user_sgpr_private_segment_size 0
		.amdhsa_uses_dynamic_stack 0
		.amdhsa_enable_private_segment 0
		.amdhsa_system_sgpr_workgroup_id_x 1
		.amdhsa_system_sgpr_workgroup_id_y 0
		.amdhsa_system_sgpr_workgroup_id_z 0
		.amdhsa_system_sgpr_workgroup_info 0
		.amdhsa_system_vgpr_workitem_id 0
		.amdhsa_next_free_vgpr 256
		.amdhsa_next_free_sgpr 102
		.amdhsa_accum_offset 256
		.amdhsa_reserve_vcc 1
		.amdhsa_float_round_mode_32 0
		.amdhsa_float_round_mode_16_64 0
		.amdhsa_float_denorm_mode_32 3
		.amdhsa_float_denorm_mode_16_64 3
		.amdhsa_dx10_clamp 1
		.amdhsa_ieee_mode 1
		.amdhsa_fp16_overflow 0
		.amdhsa_tg_split 0
		.amdhsa_exception_fp_ieee_invalid_op 0
		.amdhsa_exception_fp_denorm_src 0
		.amdhsa_exception_fp_ieee_div_zero 0
		.amdhsa_exception_fp_ieee_overflow 0
		.amdhsa_exception_fp_ieee_underflow 0
		.amdhsa_exception_fp_ieee_inexact 0
		.amdhsa_exception_int_div_zero 0
	.end_amdhsa_kernel

amdhsa.kernels:
  - .agpr_count:     0
    .args:
      - .offset:         0
        .size:           240
        .value_kind:     by_value
      - .offset:         240
        .size:           4
        .value_kind:     hidden_block_count_x
      - .offset:         244
        .size:           4
        .value_kind:     hidden_block_count_y
      - .offset:         248
        .size:           4
        .value_kind:     hidden_block_count_z
      - .offset:         252
        .size:           2
        .value_kind:     hidden_group_size_x
      - .offset:         254
        .size:           2
        .value_kind:     hidden_group_size_y
      - .offset:         256
        .size:           2
        .value_kind:     hidden_group_size_z
      - .offset:         258
        .size:           2
        .value_kind:     hidden_remainder_x
      - .offset:         260
        .size:           2
        .value_kind:     hidden_remainder_y
      - .offset:         262
        .size:           2
        .value_kind:     hidden_remainder_z
      - .offset:         280
        .size:           8
        .value_kind:     hidden_global_offset_x
      - .offset:         288
        .size:           8
        .value_kind:     hidden_global_offset_y
      - .offset:         296
        .size:           8
        .value_kind:     hidden_global_offset_z
      - .offset:         304
        .size:           2
        .value_kind:     hidden_grid_dims
      - .offset:         360
        .size:           4
        .value_kind:     hidden_dynamic_lds_size
    .group_segment_fixed_size: 0
    .kernarg_segment_align: 8
    .kernarg_segment_size: 496
    .language:       OpenCL C
    .language_version:
      - 2
      - 0
    .max_flat_workgroup_size: 512
    .name:           _Z7hyb_fwd4Args
    .private_segment_fixed_size: 0
    .sgpr_count:     108
    .sgpr_spill_count: 99
    .symbol:         _Z7hyb_fwd4Args.kd
    .uniform_work_group_size: 1
    .uses_dynamic_stack: false
    .vgpr_count:     256
    .vgpr_spill_count: 0
    .wavefront_size: 64
